# cross-lane reductions on the VALU crossbar instead of ds_bpermute LDS round trips: RES epilogue row sum-of-squares (v_permlane16_swap + v_permlane32_swap), fill_rstd pair sum (DPP quad_perm), wave_sum
# baseline (speedup 1.0000x reference)
.LBB0_47:
	s_ashr_i32 s25, s24, 31
	s_lshl_b64 s[4:5], s[24:25], 12
	v_lshl_add_u64 v[2:3], v[54:55], 0, s[4:5]
	global_load_dwordx4 v[66:69], v[2:3], off nt
	global_load_dwordx4 v[70:73], v[2:3], off offset:1024 nt
	global_load_dwordx4 v[74:77], v[2:3], off offset:2048 nt
	global_load_dwordx4 v[78:81], v[2:3], off offset:3072 nt
	s_add_i32 s12, s24, s16
	s_add_i32 s22, s3, s24
	s_add_i32 s20, s73, s24
	s_ashr_i32 s13, s12, 31
	s_ashr_i32 s23, s22, 31
	s_ashr_i32 s21, s20, 31
	s_lshl_b64 s[4:5], s[12:13], 12
	s_lshl_b64 s[26:27], s[22:23], 12
	s_lshl_b64 s[28:29], s[20:21], 12
	v_lshl_add_u64 v[82:83], v[54:55], 0, s[4:5]
	v_lshl_add_u64 v[84:85], v[54:55], 0, s[26:27]
	v_lshl_add_u64 v[86:87], v[54:55], 0, s[28:29]
	global_load_dwordx4 v[46:49], v[82:83], off nt
	global_load_dwordx4 v[42:45], v[82:83], off offset:1024 nt
	global_load_dwordx4 v[38:41], v[82:83], off offset:2048 nt
	global_load_dwordx4 v[34:37], v[82:83], off offset:3072 nt
	global_load_dwordx4 v[30:33], v[84:85], off nt
	global_load_dwordx4 v[26:29], v[84:85], off offset:1024 nt
	global_load_dwordx4 v[22:25], v[84:85], off offset:2048 nt
	global_load_dwordx4 v[18:21], v[84:85], off offset:3072 nt
	s_waitcnt lgkmcnt(0)
	global_load_dwordx4 v[14:17], v[86:87], off nt
	global_load_dwordx4 v[10:13], v[86:87], off offset:1024 nt
	global_load_dwordx4 v[6:9], v[86:87], off offset:2048 nt
	global_load_dwordx4 v[2:5], v[86:87], off offset:3072 nt
	s_lshl_b64 s[4:5], s[24:25], 11
	s_waitcnt vmcnt(15)
	v_mul_f32_e32 v51, v67, v67
	v_mul_f32_e32 v53, v69, v69
	s_waitcnt vmcnt(14)
	v_mul_f32_e32 v82, v71, v71
	v_mul_f32_e32 v83, v73, v73
	s_waitcnt vmcnt(13)
	v_mul_f32_e32 v84, v75, v75
	v_mul_f32_e32 v85, v77, v77
	v_fmac_f32_e32 v51, v66, v66
	v_fmac_f32_e32 v53, v68, v68
	v_fmac_f32_e32 v82, v70, v70
	v_fmac_f32_e32 v83, v72, v72
	s_waitcnt vmcnt(12)
	v_mul_f32_e32 v86, v79, v79
	v_mul_f32_e32 v87, v81, v81
	v_fmac_f32_e32 v84, v74, v74
	v_fmac_f32_e32 v85, v76, v76
	v_add_f32_e32 v51, v51, v53
	v_add_f32_e32 v53, v82, v83
	v_fmac_f32_e32 v86, v78, v78
	v_fmac_f32_e32 v87, v80, v80
	v_add_f32_e32 v82, v84, v85
	v_add_f32_e32 v51, v51, v53
	v_add_f32_e32 v83, v86, v87
	v_add_f32_e32 v51, v51, v82
	v_add_f32_e32 v51, v51, v83
	s_nop 1
	v_mov_b32_dpp v53, v51 quad_perm:[1,0,3,2] row_mask:0xf bank_mask:0xf
	v_lshl_add_u64 v[82:83], v[56:57], 0, s[4:5]
	v_cvt_pk_bf16_f32 v66, v66, v67
	v_cvt_pk_bf16_f32 v67, v68, v69
	v_cvt_pk_bf16_f32 v68, v70, v71
	s_waitcnt lgkmcnt(0)
	v_add_f32_e32 v51, v51, v53
	s_nop 1
	v_mov_b32_dpp v53, v51 quad_perm:[2,3,0,1] row_mask:0xf bank_mask:0xf
	v_cvt_pk_bf16_f32 v69, v72, v73
	v_cvt_pk_bf16_f32 v70, v74, v75
	global_store_dwordx2 v[82:83], v[66:67], off
	global_store_dwordx2 v[82:83], v[68:69], off offset:512
	v_cvt_pk_bf16_f32 v71, v76, v77
	s_waitcnt lgkmcnt(0)
	v_add_f32_e32 v51, v51, v53
	s_nop 1
	v_mov_b32_dpp v53, v51 row_half_mirror row_mask:0xf bank_mask:0xf
	v_cvt_pk_bf16_f32 v66, v78, v79
	v_cvt_pk_bf16_f32 v67, v80, v81
	global_store_dwordx2 v[82:83], v[70:71], off offset:1024
	global_store_dwordx2 v[82:83], v[66:67], off offset:1536
	s_waitcnt lgkmcnt(0)
	v_add_f32_e32 v51, v51, v53
	s_nop 1
	v_mov_b32_dpp v53, v51 row_mirror row_mask:0xf bank_mask:0xf
	s_waitcnt lgkmcnt(0)
	v_add_f32_e32 v51, v51, v53
	v_mov_b32_e32 v53, v51
	s_nop 1
	v_permlane16_swap_b32_e32 v51, v53
	s_waitcnt lgkmcnt(0)
	v_add_f32_e32 v51, v51, v53
	v_mov_b32_e32 v53, v51
	s_nop 1
	v_permlane32_swap_b32_e32 v51, v53
	s_and_saveexec_b64 s[26:27], vcc
	s_cbranch_execz .LBB0_49
	s_waitcnt lgkmcnt(0)
	v_add_f32_e32 v51, v51, v53
	s_lshl_b64 s[4:5], s[24:25], 6
	v_cndmask_b32_e64 v51, 0, v51, s[6:7]
	v_lshl_add_u64 v[66:67], v[58:59], 0, s[4:5]
	global_store_dword v[66:67], v51, off
.LBB0_49:
	s_or_b64 exec, exec, s[26:27]
	s_waitcnt vmcnt(15)
	v_mul_f32_e32 v51, v47, v47
	s_waitcnt lgkmcnt(0)
	v_mul_f32_e32 v53, v49, v49
	v_fmac_f32_e32 v51, v46, v46
	v_fmac_f32_e32 v53, v48, v48
	v_add_f32_e32 v51, v51, v53
	s_waitcnt vmcnt(14)
	v_mul_f32_e32 v53, v43, v43
	v_mul_f32_e32 v66, v45, v45
	v_fmac_f32_e32 v53, v42, v42
	v_fmac_f32_e32 v66, v44, v44
	v_add_f32_e32 v53, v53, v66
	v_add_f32_e32 v51, v51, v53
	s_waitcnt vmcnt(13)
	v_mul_f32_e32 v53, v39, v39
	v_mul_f32_e32 v66, v41, v41
	v_fmac_f32_e32 v53, v38, v38
	v_fmac_f32_e32 v66, v40, v40
	v_add_f32_e32 v53, v53, v66
	v_add_f32_e32 v51, v51, v53
	s_waitcnt vmcnt(12)
	v_mul_f32_e32 v53, v35, v35
	v_mul_f32_e32 v66, v37, v37
	v_fmac_f32_e32 v53, v34, v34
	v_fmac_f32_e32 v66, v36, v36
	v_add_f32_e32 v53, v53, v66
	v_add_f32_e32 v51, v51, v53
	s_nop 1
	v_mov_b32_dpp v53, v51 quad_perm:[1,0,3,2] row_mask:0xf bank_mask:0xf
	v_cvt_pk_bf16_f32 v66, v46, v47
	s_lshl_b64 s[4:5], s[12:13], 11
	v_lshl_add_u64 v[68:69], v[56:57], 0, s[4:5]
	v_cvt_pk_bf16_f32 v67, v48, v49
	s_waitcnt lgkmcnt(0)
	v_add_f32_e32 v51, v51, v53
	s_nop 1
	v_mov_b32_dpp v53, v51 quad_perm:[2,3,0,1] row_mask:0xf bank_mask:0xf
	v_cvt_pk_bf16_f32 v42, v42, v43
	v_cvt_pk_bf16_f32 v43, v44, v45
	v_cvt_pk_bf16_f32 v38, v38, v39
	v_cvt_pk_bf16_f32 v39, v40, v41
	s_waitcnt lgkmcnt(0)
	v_add_f32_e32 v51, v51, v53
	s_nop 1
	v_mov_b32_dpp v53, v51 row_half_mirror row_mask:0xf bank_mask:0xf
	v_cvt_pk_bf16_f32 v34, v34, v35
	v_cvt_pk_bf16_f32 v35, v36, v37
	global_store_dwordx2 v[68:69], v[66:67], off
	global_store_dwordx2 v[68:69], v[42:43], off offset:512
	s_waitcnt lgkmcnt(0)
	v_add_f32_e32 v51, v51, v53
	s_nop 1
	v_mov_b32_dpp v53, v51 row_mirror row_mask:0xf bank_mask:0xf
	global_store_dwordx2 v[68:69], v[38:39], off offset:1024
	global_store_dwordx2 v[68:69], v[34:35], off offset:1536
	s_waitcnt lgkmcnt(0)
	v_add_f32_e32 v51, v51, v53
	v_mov_b32_e32 v53, v51
	s_nop 1
	v_permlane16_swap_b32_e32 v51, v53
	s_waitcnt lgkmcnt(0)
	v_add_f32_e32 v46, v51, v53
	v_mov_b32_e32 v47, v46
	s_nop 1
	v_permlane32_swap_b32_e32 v46, v47
	s_and_saveexec_b64 s[24:25], vcc
	s_cbranch_execz .LBB0_51
	s_waitcnt lgkmcnt(0)
	v_add_f32_e32 v34, v46, v47
	s_lshl_b64 s[4:5], s[12:13], 6
	v_cndmask_b32_e64 v36, 0, v34, s[6:7]
	v_lshl_add_u64 v[34:35], v[58:59], 0, s[4:5]
	global_store_dword v[34:35], v36, off
.LBB0_51:
	s_or_b64 exec, exec, s[24:25]
	s_waitcnt vmcnt(15)
	v_mul_f32_e32 v34, v31, v31
	v_mul_f32_e32 v35, v33, v33
	v_fmac_f32_e32 v34, v30, v30
	v_fmac_f32_e32 v35, v32, v32
	v_add_f32_e32 v34, v34, v35
	s_waitcnt vmcnt(14)
	v_mul_f32_e32 v35, v27, v27
	v_mul_f32_e32 v36, v29, v29
	v_fmac_f32_e32 v35, v26, v26
	v_fmac_f32_e32 v36, v28, v28
	v_add_f32_e32 v35, v35, v36
	v_add_f32_e32 v34, v34, v35
	s_waitcnt vmcnt(13)
	v_mul_f32_e32 v35, v23, v23
	v_mul_f32_e32 v36, v25, v25
	v_fmac_f32_e32 v35, v22, v22
	v_fmac_f32_e32 v36, v24, v24
	v_add_f32_e32 v35, v35, v36
	v_add_f32_e32 v34, v34, v35
	s_waitcnt vmcnt(12)
	v_mul_f32_e32 v35, v19, v19
	v_mul_f32_e32 v36, v21, v21
	v_fmac_f32_e32 v35, v18, v18
	v_fmac_f32_e32 v36, v20, v20
	v_add_f32_e32 v35, v35, v36
	v_add_f32_e32 v34, v34, v35
	s_nop 1
	v_mov_b32_dpp v35, v34 quad_perm:[1,0,3,2] row_mask:0xf bank_mask:0xf
	s_lshl_b64 s[4:5], s[22:23], 11
	v_lshl_add_u64 v[36:37], v[56:57], 0, s[4:5]
	v_cvt_pk_bf16_f32 v26, v26, v27
	v_cvt_pk_bf16_f32 v27, v28, v29
	s_waitcnt lgkmcnt(0)
	v_add_f32_e32 v34, v34, v35
	s_nop 1
	v_mov_b32_dpp v35, v34 quad_perm:[2,3,0,1] row_mask:0xf bank_mask:0xf
	v_cvt_pk_bf16_f32 v22, v22, v23
	v_cvt_pk_bf16_f32 v23, v24, v25
	v_cvt_pk_bf16_f32 v18, v18, v19
	v_cvt_pk_bf16_f32 v19, v20, v21
	s_waitcnt lgkmcnt(0)
	v_add_f32_e32 v34, v34, v35
	s_nop 1
	v_mov_b32_dpp v35, v34 row_half_mirror row_mask:0xf bank_mask:0xf
	global_store_dwordx2 v[36:37], v[26:27], off offset:512
	global_store_dwordx2 v[36:37], v[22:23], off offset:1024
	global_store_dwordx2 v[36:37], v[18:19], off offset:1536
	s_waitcnt lgkmcnt(0)
	v_add_f32_e32 v34, v34, v35
	s_nop 1
	v_mov_b32_dpp v35, v34 row_mirror row_mask:0xf bank_mask:0xf
	s_waitcnt lgkmcnt(0)
	v_add_f32_e32 v35, v34, v35
	v_mov_b32_e32 v38, v35
	s_nop 1
	v_permlane16_swap_b32_e32 v35, v38
	v_cvt_pk_bf16_f32 v34, v30, v31
	s_waitcnt lgkmcnt(0)
	v_add_f32_e32 v30, v35, v38
	v_mov_b32_e32 v31, v30
	s_nop 1
	v_permlane32_swap_b32_e32 v30, v31
	v_cvt_pk_bf16_f32 v35, v32, v33
	global_store_dwordx2 v[36:37], v[34:35], off
	s_and_saveexec_b64 s[24:25], vcc
	s_cbranch_execz .LBB0_53
	s_waitcnt lgkmcnt(0)
	v_add_f32_e32 v18, v30, v31
	s_lshl_b64 s[4:5], s[22:23], 6
	v_cndmask_b32_e64 v20, 0, v18, s[6:7]
	v_lshl_add_u64 v[18:19], v[58:59], 0, s[4:5]
	global_store_dword v[18:19], v20, off
.LBB0_53:
	s_or_b64 exec, exec, s[24:25]
	s_waitcnt vmcnt(15)
	v_mul_f32_e32 v18, v15, v15
	v_mul_f32_e32 v19, v17, v17
	v_fmac_f32_e32 v18, v14, v14
	v_fmac_f32_e32 v19, v16, v16
	v_add_f32_e32 v18, v18, v19
	s_waitcnt vmcnt(14)
	v_mul_f32_e32 v19, v11, v11
	v_mul_f32_e32 v20, v13, v13
	v_fmac_f32_e32 v19, v10, v10
	v_fmac_f32_e32 v20, v12, v12
	v_add_f32_e32 v19, v19, v20
	v_add_f32_e32 v18, v18, v19
	s_waitcnt vmcnt(13)
	v_mul_f32_e32 v19, v7, v7
	v_mul_f32_e32 v20, v9, v9
	v_fmac_f32_e32 v19, v6, v6
	v_fmac_f32_e32 v20, v8, v8
	v_add_f32_e32 v19, v19, v20
	v_add_f32_e32 v18, v18, v19
	s_waitcnt vmcnt(12)
	v_mul_f32_e32 v19, v3, v3
	v_mul_f32_e32 v20, v5, v5
	v_fmac_f32_e32 v19, v2, v2
	v_fmac_f32_e32 v20, v4, v4
	v_add_f32_e32 v19, v19, v20
	v_add_f32_e32 v18, v18, v19
	s_nop 1
	v_mov_b32_dpp v19, v18 quad_perm:[1,0,3,2] row_mask:0xf bank_mask:0xf
	s_lshl_b64 s[4:5], s[20:21], 11
	v_lshl_add_u64 v[20:21], v[56:57], 0, s[4:5]
	v_cvt_pk_bf16_f32 v10, v10, v11
	v_cvt_pk_bf16_f32 v11, v12, v13
	s_waitcnt lgkmcnt(0)
	v_add_f32_e32 v18, v18, v19
	s_nop 1
	v_mov_b32_dpp v19, v18 quad_perm:[2,3,0,1] row_mask:0xf bank_mask:0xf
	v_cvt_pk_bf16_f32 v6, v6, v7
	v_cvt_pk_bf16_f32 v7, v8, v9
	v_cvt_pk_bf16_f32 v2, v2, v3
	v_cvt_pk_bf16_f32 v3, v4, v5
	s_waitcnt lgkmcnt(0)
	v_add_f32_e32 v18, v18, v19
	s_nop 1
	v_mov_b32_dpp v19, v18 row_half_mirror row_mask:0xf bank_mask:0xf
	global_store_dwordx2 v[20:21], v[10:11], off offset:512
	global_store_dwordx2 v[20:21], v[6:7], off offset:1024
	global_store_dwordx2 v[20:21], v[2:3], off offset:1536
	s_waitcnt lgkmcnt(0)
	v_add_f32_e32 v18, v18, v19
	s_nop 1
	v_mov_b32_dpp v19, v18 row_mirror row_mask:0xf bank_mask:0xf
	s_waitcnt lgkmcnt(0)
	v_add_f32_e32 v19, v18, v19
	v_mov_b32_e32 v22, v19
	s_nop 1
	v_permlane16_swap_b32_e32 v19, v22
	v_cvt_pk_bf16_f32 v18, v14, v15
	s_waitcnt lgkmcnt(0)
	v_add_f32_e32 v14, v19, v22
	v_mov_b32_e32 v15, v14
	s_nop 1
	v_permlane32_swap_b32_e32 v14, v15
	v_cvt_pk_bf16_f32 v19, v16, v17
	global_store_dwordx2 v[20:21], v[18:19], off
	s_and_saveexec_b64 s[22:23], vcc
	s_cbranch_execz .LBB0_46
	s_waitcnt lgkmcnt(0)
	v_add_f32_e32 v2, v14, v15
	s_lshl_b64 s[4:5], s[20:21], 6
	v_cndmask_b32_e64 v4, 0, v2, s[6:7]
	v_lshl_add_u64 v[2:3], v[58:59], 0, s[4:5]
	global_store_dword v[2:3], v4, off
	s_branch .LBB0_46

.LBB0_57:
	global_load_dwordx4 v[16:19], v[6:7], off offset:-2048
	global_load_dwordx4 v[20:23], v[6:7], off offset:-1024
	global_load_dwordx4 v[24:27], v[6:7], off
	global_load_dwordx4 v[28:31], v[6:7], off offset:1024
	global_load_dwordx4 v[32:35], v[2:3], off
	s_add_i32 s8, s8, s16
	v_lshl_add_u64 v[6:7], v[6:7], 0, s[12:13]
	s_cmpk_lt_i32 s8, 0x200
	s_waitcnt vmcnt(4)
	v_pk_mul_f32 v[36:37], v[18:19], v[18:19]
	v_pk_mul_f32 v[38:39], v[16:17], v[16:17]
	s_waitcnt vmcnt(3)
	v_pk_mul_f32 v[40:41], v[22:23], v[22:23]
	v_pk_mul_f32 v[42:43], v[20:21], v[20:21]
	v_pk_mov_b32 v[48:49], v[38:39], v[36:37] op_sel:[1,0]
	v_mov_b32_e32 v39, v37
	v_pk_mov_b32 v[36:37], v[42:43], v[40:41] op_sel:[1,0]
	v_mov_b32_e32 v43, v41
	s_waitcnt vmcnt(1)
	v_mul_f32_e32 v47, v28, v28
	v_mul_f32_e32 v44, v25, v25
	v_mul_f32_e32 v46, v27, v27
	v_pk_add_f32 v[38:39], v[48:49], v[38:39]
	v_pk_add_f32 v[36:37], v[36:37], v[42:43]
	v_mul_f32_e32 v50, v29, v29
	v_mul_f32_e32 v51, v30, v30
	v_mul_f32_e32 v52, v31, v31
	v_pk_fma_f32 v[40:41], v[24:25], v[24:25], v[44:45] op_sel_hi:[1,1,0]
	v_pk_fma_f32 v[44:45], v[26:27], v[26:27], v[46:47] op_sel_hi:[1,1,0]
	v_pk_add_f32 v[38:39], v[38:39], v[38:39] op_sel:[0,1] op_sel_hi:[1,0]
	v_pk_add_f32 v[36:37], v[36:37], v[36:37] op_sel:[0,1] op_sel_hi:[1,0]
	v_mov_b32_e32 v41, v51
	v_mov_b32_e32 v45, v52
	v_mov_b32_e32 v39, v47
	v_mov_b32_e32 v37, v50
	v_pk_add_f32 v[40:41], v[40:41], v[44:45]
	v_pk_add_f32 v[36:37], v[38:39], v[36:37]
	s_nop 0
	v_pk_add_f32 v[36:37], v[36:37], v[40:41]
	s_nop 0
	v_add_f32_e32 v36, v36, v37
	s_nop 1
	v_mov_b32_dpp v37, v36 quad_perm:[1,0,3,2] row_mask:0xf bank_mask:0xf
	s_waitcnt lgkmcnt(0)
	v_add_f32_e32 v36, v36, v37
	s_nop 1
	v_mov_b32_dpp v37, v36 quad_perm:[2,3,0,1] row_mask:0xf bank_mask:0xf
	s_waitcnt lgkmcnt(0)
	v_add_f32_e32 v36, v36, v37
	s_nop 1
	v_mov_b32_dpp v37, v36 row_half_mirror row_mask:0xf bank_mask:0xf
	s_waitcnt lgkmcnt(0)
	v_add_f32_e32 v36, v36, v37
	s_nop 1
	v_mov_b32_dpp v37, v36 row_mirror row_mask:0xf bank_mask:0xf
	s_waitcnt lgkmcnt(0)
	v_add_f32_e32 v36, v36, v37
	v_mov_b32_e32 v37, v36
	s_nop 1
	v_permlane16_swap_b32_e32 v36, v37
	s_waitcnt lgkmcnt(0)
	v_add_f32_e32 v36, v36, v37
	v_mov_b32_e32 v37, v36
	s_nop 1
	v_permlane32_swap_b32_e32 v36, v37
	s_waitcnt lgkmcnt(0)
	v_add_f32_e32 v36, v36, v37
	v_fmamk_f32 v36, v36, 0x3a800000, v14
	v_mul_f32_e32 v37, 0x4f800000, v36
	v_cmp_gt_f32_e32 vcc, s3, v36
	s_nop 1
	v_cndmask_b32_e32 v36, v36, v37, vcc
	v_sqrt_f32_e32 v37, v36
	s_nop 0
	v_add_u32_e32 v38, -1, v37
	v_add_u32_e32 v39, 1, v37
	v_fma_f32 v40, -v38, v37, v36
	v_fma_f32 v41, -v39, v37, v36
	v_cmp_ge_f32_e64 s[6:7], 0, v40
	s_nop 1
	v_cndmask_b32_e64 v37, v37, v38, s[6:7]
	v_cmp_lt_f32_e64 s[6:7], 0, v41
	s_nop 1
	v_cndmask_b32_e64 v37, v37, v39, s[6:7]
	v_mul_f32_e32 v38, 0x37800000, v37
	v_cndmask_b32_e32 v37, v37, v38, vcc
	v_cmp_class_f32_e32 vcc, v36, v15
	s_nop 1
	v_cndmask_b32_e32 v36, v37, v36, vcc
	v_div_scale_f32 v37, s[4:5], v36, v36, 1.0
	v_rcp_f32_e32 v39, v37
	v_div_scale_f32 v38, vcc, 1.0, v36, 1.0
	v_fma_f32 v40, -v37, v39, 1.0
	v_fmac_f32_e32 v39, v40, v39
	v_mul_f32_e32 v40, v38, v39
	v_fma_f32 v41, -v37, v40, v38
	v_fmac_f32_e32 v40, v41, v39
	v_fma_f32 v37, -v37, v40, v38
	v_div_fmas_f32 v37, v37, v39, v40
	v_div_fixup_f32 v36, v37, v36, 1.0
	v_pk_mul_f32 v[16:17], v[16:17], v[36:37] op_sel_hi:[1,0]
	v_pk_mul_f32 v[18:19], v[18:19], v[36:37] op_sel_hi:[1,0]
	s_waitcnt vmcnt(0)
	v_pk_mul_f32 v[16:17], v[32:33], v[16:17]
	v_pk_mul_f32 v[18:19], v[34:35], v[18:19]
	v_cvt_pk_bf16_f32 v16, v16, v17
	v_cvt_pk_bf16_f32 v17, v18, v19
	global_store_dwordx2 v[4:5], v[16:17], off offset:-1536
	global_load_dwordx4 v[16:19], v[2:3], off offset:1024
	v_pk_mul_f32 v[20:21], v[20:21], v[36:37] op_sel_hi:[1,0]
	v_pk_mul_f32 v[22:23], v[22:23], v[36:37] op_sel_hi:[1,0]
	s_waitcnt vmcnt(0)
	v_pk_mul_f32 v[16:17], v[16:17], v[20:21]
	v_pk_mul_f32 v[18:19], v[18:19], v[22:23]
	v_cvt_pk_bf16_f32 v16, v16, v17
	v_cvt_pk_bf16_f32 v17, v18, v19
	global_store_dwordx2 v[4:5], v[16:17], off offset:-1024
	global_load_dwordx4 v[16:19], v[2:3], off offset:2048
	v_pk_mul_f32 v[20:21], v[24:25], v[36:37] op_sel_hi:[1,0]
	v_pk_mul_f32 v[22:23], v[26:27], v[36:37] op_sel_hi:[1,0]
	s_waitcnt vmcnt(0)
	v_pk_mul_f32 v[16:17], v[16:17], v[20:21]
	v_pk_mul_f32 v[18:19], v[18:19], v[22:23]
	v_cvt_pk_bf16_f32 v16, v16, v17
	v_cvt_pk_bf16_f32 v17, v18, v19
	global_store_dwordx2 v[4:5], v[16:17], off offset:-512
	global_load_dwordx4 v[16:19], v[2:3], off offset:3072
	v_pk_mul_f32 v[20:21], v[28:29], v[36:37] op_sel_hi:[1,0]
	v_pk_mul_f32 v[22:23], v[30:31], v[36:37] op_sel_hi:[1,0]
	s_waitcnt vmcnt(0)
	v_pk_mul_f32 v[16:17], v[16:17], v[20:21]
	v_pk_mul_f32 v[18:19], v[18:19], v[22:23]
	v_cvt_pk_bf16_f32 v16, v16, v17
	v_cvt_pk_bf16_f32 v17, v18, v19
	global_store_dwordx2 v[4:5], v[16:17], off
	v_lshl_add_u64 v[4:5], v[4:5], 0, s[10:11]
	s_cbranch_scc1 .LBB0_57

.LBB0_129:
	s_ashr_i32 s7, s6, 31
	s_lshl_b64 s[4:5], s[6:7], 11
	v_lshl_add_u64 v[2:3], v[6:7], 0, s[4:5]
	global_load_dwordx2 v[4:5], v[2:3], off nt
	global_load_dwordx2 v[36:37], v[2:3], off offset:512 nt
	global_load_dwordx2 v[38:39], v[2:3], off offset:1024 nt
	s_nop 0
	global_load_dwordx2 v[2:3], v[2:3], off offset:1536 nt
	s_add_i32 s12, s6, s16
	s_ashr_i32 s13, s12, 31
	s_add_i32 s92, s95, s6
	s_lshl_b64 s[4:5], s[12:13], 11
	s_ashr_i32 s93, s92, 31
	v_lshl_add_u64 v[12:13], v[6:7], 0, s[4:5]
	s_add_i32 s8, s12, s16
	s_lshl_b64 s[4:5], s[92:93], 11
	global_load_dwordx2 v[34:35], v[12:13], off nt
	global_load_dwordx2 v[32:33], v[12:13], off offset:512 nt
	global_load_dwordx2 v[30:31], v[12:13], off offset:1024 nt
	global_load_dwordx2 v[28:29], v[12:13], off offset:1536 nt
	v_lshl_add_u64 v[12:13], v[6:7], 0, s[4:5]
	s_add_i32 s4, s8, s16
	s_add_i32 s8, s73, s6
	s_lshl_b64 s[6:7], s[6:7], 12
	s_ashr_i32 s9, s8, 31
	s_lshl_b64 s[22:23], s[8:9], 11
	global_load_dwordx2 v[26:27], v[12:13], off nt
	global_load_dwordx2 v[24:25], v[12:13], off offset:512 nt
	global_load_dwordx2 v[22:23], v[12:13], off offset:1024 nt
	global_load_dwordx2 v[20:21], v[12:13], off offset:1536 nt
	v_lshl_add_u64 v[12:13], v[6:7], 0, s[22:23]
	global_load_dwordx2 v[18:19], v[12:13], off nt
	global_load_dwordx2 v[16:17], v[12:13], off offset:512 nt
	global_load_dwordx2 v[14:15], v[12:13], off offset:1024 nt
	s_nop 0
	global_load_dwordx2 v[12:13], v[12:13], off offset:1536 nt
	s_waitcnt vmcnt(0)
	v_lshlrev_b32_e32 v52, 16, v4
	s_waitcnt vmcnt(14)
	v_and_b32_e32 v51, 0xffff0000, v37
	v_and_b32_e32 v50, 0xffff0000, v36
	v_and_b32_e32 v53, 0xffff0000, v4
	v_lshlrev_b32_e32 v4, 16, v5
	v_and_b32_e32 v5, 0xffff0000, v5
	v_lshlrev_b32_e32 v49, 16, v37
	v_lshlrev_b32_e32 v48, 16, v36
	v_pk_mul_f32 v[36:37], v[50:51], v[50:51]
	v_mul_f32_e32 v40, v5, v5
	v_pk_fma_f32 v[54:55], v[48:49], v[48:49], v[36:37]
	s_waitcnt vmcnt(13)
	v_lshlrev_b32_e32 v46, 16, v39
	v_and_b32_e32 v47, 0xffff0000, v39
	s_waitcnt vmcnt(12)
	v_lshlrev_b32_e32 v39, 16, v2
	v_and_b32_e32 v37, 0xffff0000, v2
	v_mul_f32_e32 v2, v53, v53
	v_pk_fma_f32 v[42:43], v[4:5], v[4:5], v[40:41] op_sel_hi:[1,1,0]
	v_lshlrev_b32_e32 v40, 16, v3
	v_and_b32_e32 v41, 0xffff0000, v3
	v_pk_fma_f32 v[2:3], v[52:53], v[52:53], v[2:3] op_sel_hi:[1,1,0]
	v_lshlrev_b32_e32 v44, 16, v38
	v_and_b32_e32 v45, 0xffff0000, v38
	v_mov_b32_e32 v38, v2
	v_mov_b32_e32 v62, v42
	v_mov_b32_e32 v63, v39
	v_pk_add_f32 v[2:3], v[2:3], v[42:43]
	v_pk_mul_f32 v[42:43], v[38:39], v[62:63]
	v_mul_f32_e32 v36, v37, v37
	v_mov_b32_e32 v3, v43
	v_pk_add_f32 v[42:43], v[54:55], v[54:55] op_sel:[0,1] op_sel_hi:[1,0]
	v_mul_f32_e32 v64, v40, v40
	v_mov_b32_e32 v43, v36
	v_mul_f32_e32 v36, v45, v45
	v_pk_add_f32 v[2:3], v[2:3], v[42:43]
	v_pk_fma_f32 v[42:43], v[44:45], v[44:45], v[36:37] op_sel_hi:[1,1,0]
	v_mul_f32_e32 v36, v47, v47
	v_mul_f32_e32 v65, v41, v41
	v_pk_fma_f32 v[54:55], v[46:47], v[46:47], v[36:37] op_sel_hi:[1,1,0]
	v_mov_b32_e32 v43, v64
	v_mov_b32_e32 v55, v65
	v_pk_add_f32 v[42:43], v[42:43], v[54:55]
	s_nop 0
	v_pk_add_f32 v[2:3], v[2:3], v[42:43]
	v_lshl_add_u64 v[42:43], v[10:11], 0, s[6:7]
	v_add_f32_e32 v2, v2, v3
	s_nop 1
	v_mov_b32_dpp v3, v2 quad_perm:[1,0,3,2] row_mask:0xf bank_mask:0xf
	s_waitcnt lgkmcnt(0)
	v_add_f32_e32 v2, v2, v3
	s_nop 1
	v_mov_b32_dpp v3, v2 quad_perm:[2,3,0,1] row_mask:0xf bank_mask:0xf
	s_waitcnt lgkmcnt(0)
	v_add_f32_e32 v2, v2, v3
	s_nop 1
	v_mov_b32_dpp v3, v2 row_half_mirror row_mask:0xf bank_mask:0xf
	s_waitcnt lgkmcnt(0)
	v_add_f32_e32 v2, v2, v3
	s_nop 1
	v_mov_b32_dpp v3, v2 row_mirror row_mask:0xf bank_mask:0xf
	s_waitcnt lgkmcnt(0)
	v_add_f32_e32 v2, v2, v3
	v_mov_b32_e32 v3, v2
	s_nop 1
	v_permlane16_swap_b32_e32 v2, v3
	s_waitcnt lgkmcnt(0)
	v_add_f32_e32 v2, v2, v3
	v_mov_b32_e32 v3, v2
	s_nop 1
	v_permlane32_swap_b32_e32 v2, v3
	s_waitcnt lgkmcnt(0)
	v_add_f32_e32 v2, v2, v3
	v_fmamk_f32 v2, v2, 0x3a800000, v166
	v_cmp_gt_f32_e32 vcc, s15, v2
	v_mul_f32_e32 v3, 0x4f800000, v2
	s_nop 0
	v_cndmask_b32_e32 v2, v2, v3, vcc
	v_sqrt_f32_e32 v3, v2
	s_nop 0
	v_add_u32_e32 v36, -1, v3
	v_fma_f32 v38, -v36, v3, v2
	v_cmp_ge_f32_e64 s[6:7], 0, v38
	v_add_u32_e32 v38, 1, v3
	s_nop 0
	v_cndmask_b32_e64 v36, v3, v36, s[6:7]
	v_fma_f32 v3, -v38, v3, v2
	v_cmp_lt_f32_e64 s[6:7], 0, v3
	s_nop 1
	v_cndmask_b32_e64 v3, v36, v38, s[6:7]
	v_mul_f32_e32 v36, 0x37800000, v3
	v_cndmask_b32_e32 v3, v3, v36, vcc
	v_cmp_class_f32_e32 vcc, v2, v167
	s_nop 1
	v_cndmask_b32_e32 v2, v3, v2, vcc
	v_div_scale_f32 v3, s[6:7], v2, v2, 1.0
	v_rcp_f32_e32 v36, v3
	s_lshl_b64 s[6:7], s[12:13], 12
	v_fma_f32 v38, -v3, v36, 1.0
	v_fmac_f32_e32 v36, v38, v36
	v_div_scale_f32 v38, vcc, 1.0, v2, 1.0
	v_mul_f32_e32 v54, v38, v36
	v_fma_f32 v55, -v3, v54, v38
	v_fmac_f32_e32 v54, v55, v36
	v_fma_f32 v3, -v3, v54, v38
	v_div_fmas_f32 v3, v3, v36, v54
	v_div_fixup_f32 v38, v3, v2, 1.0
	v_pk_mul_f32 v[54:55], v[38:39], v[4:5] op_sel_hi:[0,1]
	global_load_dwordx4 v[2:5], v[8:9], off
	v_pk_mul_f32 v[52:53], v[38:39], v[52:53] op_sel_hi:[0,1]
	v_pk_mul_f32 v[46:47], v[38:39], v[46:47] op_sel_hi:[0,1]
	v_pk_mul_f32 v[44:45], v[38:39], v[44:45] op_sel_hi:[0,1]
	v_mov_b32_e32 v36, v39
	v_pk_mul_f32 v[40:41], v[40:41], v[38:39] op_sel_hi:[1,0]
	v_pk_mul_f32 v[36:37], v[36:37], v[38:39] op_sel_hi:[1,0]
	s_waitcnt vmcnt(0)
	v_pk_mul_f32 v[4:5], v[4:5], v[54:55]
	v_pk_mul_f32 v[2:3], v[2:3], v[52:53]
	global_store_dwordx4 v[42:43], v[2:5], off nt
	s_nop 1
	v_mov_b32_e32 v2, v49
	v_mov_b32_e32 v3, v51
	v_pk_mul_f32 v[52:53], v[38:39], v[2:3] op_sel_hi:[0,1]
	global_load_dwordx4 v[2:5], v[8:9], off offset:1024
	v_mov_b32_e32 v49, v50
	v_pk_mul_f32 v[48:49], v[38:39], v[48:49] op_sel_hi:[0,1]
	s_waitcnt vmcnt(0)
	v_pk_mul_f32 v[2:3], v[2:3], v[48:49]
	v_pk_mul_f32 v[4:5], v[4:5], v[52:53]
	global_store_dwordx4 v[42:43], v[2:5], off offset:1024 nt
	global_load_dwordx4 v[2:5], v[8:9], off offset:2048
	s_waitcnt vmcnt(0)
	v_pk_mul_f32 v[2:3], v[2:3], v[44:45]
	v_pk_mul_f32 v[4:5], v[4:5], v[46:47]
	global_store_dwordx4 v[42:43], v[2:5], off offset:2048 nt
	global_load_dwordx4 v[2:5], v[8:9], off offset:3072
	s_waitcnt vmcnt(0)
	v_pk_mul_f32 v[2:3], v[2:3], v[36:37]
	v_pk_mul_f32 v[4:5], v[4:5], v[40:41]
	v_and_b32_e32 v41, 0xffff0000, v35
	global_store_dwordx4 v[42:43], v[2:5], off offset:3072 nt
	v_lshlrev_b32_e32 v40, 16, v35
	v_and_b32_e32 v37, 0xffff0000, v33
	v_mul_f32_e32 v2, v41, v41
	v_and_b32_e32 v36, 0xffff0000, v32
	v_lshlrev_b32_e32 v42, 16, v34
	v_and_b32_e32 v43, 0xffff0000, v34
	v_pk_fma_f32 v[38:39], v[40:41], v[40:41], v[2:3] op_sel_hi:[1,1,0]
	v_lshlrev_b32_e32 v35, 16, v33
	v_lshlrev_b32_e32 v34, 16, v32
	v_pk_mul_f32 v[2:3], v[36:37], v[36:37]
	v_lshlrev_b32_e32 v5, 16, v28
	v_pk_fma_f32 v[44:45], v[34:35], v[34:35], v[2:3]
	v_and_b32_e32 v3, 0xffff0000, v28
	v_mul_f32_e32 v2, v43, v43
	v_pk_fma_f32 v[46:47], v[42:43], v[42:43], v[2:3] op_sel_hi:[1,1,0]
	v_mov_b32_e32 v48, v38
	v_mov_b32_e32 v4, v46
	v_mov_b32_e32 v49, v5
	v_and_b32_e32 v33, 0xffff0000, v30
	v_mul_f32_e32 v50, v3, v3
	v_pk_add_f32 v[38:39], v[46:47], v[38:39]
	v_pk_mul_f32 v[46:47], v[4:5], v[48:49]
	v_pk_add_f32 v[44:45], v[44:45], v[44:45] op_sel:[0,1] op_sel_hi:[1,0]
	v_lshlrev_b32_e32 v32, 16, v30
	v_lshlrev_b32_e32 v30, 16, v31
	v_and_b32_e32 v31, 0xffff0000, v31
	v_mov_b32_e32 v39, v47
	v_mov_b32_e32 v45, v50
	v_mul_f32_e32 v2, v33, v33
	v_lshlrev_b32_e32 v28, 16, v29
	v_and_b32_e32 v29, 0xffff0000, v29
	v_pk_add_f32 v[38:39], v[38:39], v[44:45]
	v_pk_fma_f32 v[44:45], v[32:33], v[32:33], v[2:3] op_sel_hi:[1,1,0]
	v_mul_f32_e32 v2, v31, v31
	v_mul_f32_e32 v51, v28, v28
	v_mul_f32_e32 v52, v29, v29
	v_pk_fma_f32 v[46:47], v[30:31], v[30:31], v[2:3] op_sel_hi:[1,1,0]
	v_mov_b32_e32 v45, v51
	v_mov_b32_e32 v47, v52
	v_pk_add_f32 v[44:45], v[44:45], v[46:47]
	s_nop 0
	v_pk_add_f32 v[38:39], v[38:39], v[44:45]
	s_nop 0
	v_add_f32_e32 v2, v38, v39
	s_nop 1
	v_mov_b32_dpp v4, v2 quad_perm:[1,0,3,2] row_mask:0xf bank_mask:0xf
	v_lshl_add_u64 v[38:39], v[10:11], 0, s[6:7]
	s_waitcnt lgkmcnt(0)
	v_add_f32_e32 v2, v2, v4
	s_nop 1
	v_mov_b32_dpp v4, v2 quad_perm:[2,3,0,1] row_mask:0xf bank_mask:0xf
	s_waitcnt lgkmcnt(0)
	v_add_f32_e32 v2, v2, v4
	s_nop 1
	v_mov_b32_dpp v4, v2 row_half_mirror row_mask:0xf bank_mask:0xf
	s_waitcnt lgkmcnt(0)
	v_add_f32_e32 v2, v2, v4
	s_nop 1
	v_mov_b32_dpp v4, v2 row_mirror row_mask:0xf bank_mask:0xf
	s_waitcnt lgkmcnt(0)
	v_add_f32_e32 v2, v2, v4
	v_mov_b32_e32 v4, v2
	s_nop 1
	v_permlane16_swap_b32_e32 v2, v4
	s_waitcnt lgkmcnt(0)
	v_add_f32_e32 v2, v2, v4
	v_mov_b32_e32 v4, v2
	s_nop 1
	v_permlane32_swap_b32_e32 v2, v4
	s_waitcnt lgkmcnt(0)
	v_add_f32_e32 v2, v2, v4
	v_fmamk_f32 v2, v2, 0x3a800000, v166
	v_cmp_gt_f32_e32 vcc, s15, v2
	v_mul_f32_e32 v4, 0x4f800000, v2
	s_nop 0
	v_cndmask_b32_e32 v2, v2, v4, vcc
	v_sqrt_f32_e32 v4, v2
	s_nop 0
	v_add_u32_e32 v44, -1, v4
	v_fma_f32 v45, -v44, v4, v2
	v_cmp_ge_f32_e64 s[6:7], 0, v45
	v_add_u32_e32 v45, 1, v4
	s_nop 0
	v_cndmask_b32_e64 v44, v4, v44, s[6:7]
	v_fma_f32 v4, -v45, v4, v2
	v_cmp_lt_f32_e64 s[6:7], 0, v4
	s_nop 1
	v_cndmask_b32_e64 v4, v44, v45, s[6:7]
	v_mul_f32_e32 v44, 0x37800000, v4
	v_cndmask_b32_e32 v4, v4, v44, vcc
	v_cmp_class_f32_e32 vcc, v2, v167
	s_nop 1
	v_cndmask_b32_e32 v2, v4, v2, vcc
	v_div_scale_f32 v4, s[6:7], v2, v2, 1.0
	v_rcp_f32_e32 v44, v4
	s_lshl_b64 s[6:7], s[92:93], 12
	v_fma_f32 v45, -v4, v44, 1.0
	v_fmac_f32_e32 v44, v45, v44
	v_div_scale_f32 v45, vcc, 1.0, v2, 1.0
	v_mul_f32_e32 v46, v45, v44
	v_fma_f32 v47, -v4, v46, v45
	v_fmac_f32_e32 v46, v47, v44
	v_fma_f32 v4, -v4, v46, v45
	v_div_fmas_f32 v4, v4, v44, v46
	global_load_dwordx4 v[44:47], v[8:9], off
	v_div_fixup_f32 v4, v4, v2, 1.0
	v_pk_mul_f32 v[40:41], v[4:5], v[40:41] op_sel_hi:[0,1]
	v_pk_mul_f32 v[42:43], v[4:5], v[42:43] op_sel_hi:[0,1]
	v_mov_b32_e32 v2, v5
	v_pk_mul_f32 v[28:29], v[28:29], v[4:5] op_sel_hi:[1,0]
	s_waitcnt vmcnt(0)
	v_pk_mul_f32 v[42:43], v[44:45], v[42:43]
	v_pk_mul_f32 v[44:45], v[46:47], v[40:41]
	global_store_dwordx4 v[38:39], v[42:45], off nt
	v_mov_b32_e32 v40, v35
	v_mov_b32_e32 v35, v36
	v_mov_b32_e32 v41, v37
	v_pk_mul_f32 v[42:43], v[4:5], v[34:35] op_sel_hi:[0,1]
	global_load_dwordx4 v[34:37], v[8:9], off offset:1024
	v_pk_mul_f32 v[40:41], v[4:5], v[40:41] op_sel_hi:[0,1]
	s_waitcnt vmcnt(0)
	v_pk_mul_f32 v[34:35], v[34:35], v[42:43]
	v_pk_mul_f32 v[36:37], v[36:37], v[40:41]
	global_store_dwordx4 v[38:39], v[34:37], off offset:1024 nt
	s_nop 1
	v_pk_mul_f32 v[34:35], v[4:5], v[30:31] op_sel_hi:[0,1]
	v_pk_mul_f32 v[36:37], v[4:5], v[32:33] op_sel_hi:[0,1]
	global_load_dwordx4 v[30:33], v[8:9], off offset:2048
	s_waitcnt vmcnt(0)
	v_pk_mul_f32 v[30:31], v[30:31], v[36:37]
	v_pk_mul_f32 v[32:33], v[32:33], v[34:35]
	global_store_dwordx4 v[38:39], v[30:33], off offset:2048 nt
	v_lshlrev_b32_e32 v34, 16, v26
	v_and_b32_e32 v35, 0xffff0000, v26
	v_pk_mul_f32 v[30:31], v[2:3], v[4:5] op_sel_hi:[1,0]
	global_load_dwordx4 v[2:5], v[8:9], off offset:3072
	v_and_b32_e32 v33, 0xffff0000, v27
	v_lshlrev_b32_e32 v32, 16, v27
	v_lshlrev_b32_e32 v27, 16, v25
	v_lshlrev_b32_e32 v26, 16, v24
	s_waitcnt vmcnt(0)
	v_pk_mul_f32 v[2:3], v[2:3], v[30:31]
	v_pk_mul_f32 v[4:5], v[4:5], v[28:29]
	global_store_dwordx4 v[38:39], v[2:5], off offset:3072 nt
	v_and_b32_e32 v29, 0xffff0000, v25
	v_and_b32_e32 v28, 0xffff0000, v24
	v_mul_f32_e32 v2, v33, v33
	v_pk_fma_f32 v[30:31], v[32:33], v[32:33], v[2:3] op_sel_hi:[1,1,0]
	v_pk_mul_f32 v[2:3], v[28:29], v[28:29]
	v_lshlrev_b32_e32 v5, 16, v20
	v_pk_fma_f32 v[36:37], v[26:27], v[26:27], v[2:3]
	v_and_b32_e32 v3, 0xffff0000, v20
	v_mul_f32_e32 v2, v35, v35
	v_pk_fma_f32 v[38:39], v[34:35], v[34:35], v[2:3] op_sel_hi:[1,1,0]
	v_mov_b32_e32 v40, v30
	v_mov_b32_e32 v4, v38
	v_mov_b32_e32 v41, v5
	v_and_b32_e32 v25, 0xffff0000, v22
	v_mul_f32_e32 v42, v3, v3
	v_pk_add_f32 v[30:31], v[38:39], v[30:31]
	v_pk_mul_f32 v[38:39], v[4:5], v[40:41]
	v_pk_add_f32 v[36:37], v[36:37], v[36:37] op_sel:[0,1] op_sel_hi:[1,0]
	v_lshlrev_b32_e32 v24, 16, v22
	v_lshlrev_b32_e32 v22, 16, v23
	v_and_b32_e32 v23, 0xffff0000, v23
	v_mov_b32_e32 v31, v39
	v_mov_b32_e32 v37, v42
	v_mul_f32_e32 v2, v25, v25
	v_lshlrev_b32_e32 v20, 16, v21
	v_and_b32_e32 v21, 0xffff0000, v21
	v_pk_add_f32 v[30:31], v[30:31], v[36:37]
	v_pk_fma_f32 v[36:37], v[24:25], v[24:25], v[2:3] op_sel_hi:[1,1,0]
	v_mul_f32_e32 v2, v23, v23
	v_mul_f32_e32 v43, v20, v20
	v_mul_f32_e32 v44, v21, v21
	v_pk_fma_f32 v[38:39], v[22:23], v[22:23], v[2:3] op_sel_hi:[1,1,0]
	v_mov_b32_e32 v37, v43
	v_mov_b32_e32 v39, v44
	v_pk_add_f32 v[36:37], v[36:37], v[38:39]
	s_nop 0
	v_pk_add_f32 v[30:31], v[30:31], v[36:37]
	s_nop 0
	v_add_f32_e32 v2, v30, v31
	s_nop 1
	v_mov_b32_dpp v4, v2 quad_perm:[1,0,3,2] row_mask:0xf bank_mask:0xf
	v_lshl_add_u64 v[30:31], v[10:11], 0, s[6:7]
	s_waitcnt lgkmcnt(0)
	v_add_f32_e32 v2, v2, v4
	s_nop 1
	v_mov_b32_dpp v4, v2 quad_perm:[2,3,0,1] row_mask:0xf bank_mask:0xf
	s_waitcnt lgkmcnt(0)
	v_add_f32_e32 v2, v2, v4
	s_nop 1
	v_mov_b32_dpp v4, v2 row_half_mirror row_mask:0xf bank_mask:0xf
	s_waitcnt lgkmcnt(0)
	v_add_f32_e32 v2, v2, v4
	s_nop 1
	v_mov_b32_dpp v4, v2 row_mirror row_mask:0xf bank_mask:0xf
	s_waitcnt lgkmcnt(0)
	v_add_f32_e32 v2, v2, v4
	v_mov_b32_e32 v4, v2
	s_nop 1
	v_permlane16_swap_b32_e32 v2, v4
	s_waitcnt lgkmcnt(0)
	v_add_f32_e32 v2, v2, v4
	v_mov_b32_e32 v4, v2
	s_nop 1
	v_permlane32_swap_b32_e32 v2, v4
	s_waitcnt lgkmcnt(0)
	v_add_f32_e32 v2, v2, v4
	v_fmamk_f32 v2, v2, 0x3a800000, v166
	v_cmp_gt_f32_e32 vcc, s15, v2
	v_mul_f32_e32 v4, 0x4f800000, v2
	s_nop 0
	v_cndmask_b32_e32 v2, v2, v4, vcc
	v_sqrt_f32_e32 v4, v2
	s_nop 0
	v_add_u32_e32 v36, -1, v4
	v_fma_f32 v37, -v36, v4, v2
	v_cmp_ge_f32_e64 s[6:7], 0, v37
	v_add_u32_e32 v37, 1, v4
	s_nop 0
	v_cndmask_b32_e64 v36, v4, v36, s[6:7]
	v_fma_f32 v4, -v37, v4, v2
	v_cmp_lt_f32_e64 s[6:7], 0, v4
	s_nop 1
	v_cndmask_b32_e64 v4, v36, v37, s[6:7]
	v_mul_f32_e32 v36, 0x37800000, v4
	v_cndmask_b32_e32 v4, v4, v36, vcc
	v_cmp_class_f32_e32 vcc, v2, v167
	s_nop 1
	v_cndmask_b32_e32 v2, v4, v2, vcc
	v_div_scale_f32 v4, s[6:7], v2, v2, 1.0
	v_rcp_f32_e32 v36, v4
	s_lshl_b64 s[6:7], s[8:9], 12
	v_fma_f32 v37, -v4, v36, 1.0
	v_fmac_f32_e32 v36, v37, v36
	v_div_scale_f32 v37, vcc, 1.0, v2, 1.0
	v_mul_f32_e32 v38, v37, v36
	v_fma_f32 v39, -v4, v38, v37
	v_fmac_f32_e32 v38, v39, v36
	v_fma_f32 v4, -v4, v38, v37
	v_div_fmas_f32 v4, v4, v36, v38
	global_load_dwordx4 v[36:39], v[8:9], off
	v_div_fixup_f32 v4, v4, v2, 1.0
	v_pk_mul_f32 v[32:33], v[4:5], v[32:33] op_sel_hi:[0,1]
	v_pk_mul_f32 v[34:35], v[4:5], v[34:35] op_sel_hi:[0,1]
	v_mov_b32_e32 v2, v5
	v_pk_mul_f32 v[20:21], v[20:21], v[4:5] op_sel_hi:[1,0]
	s_waitcnt vmcnt(0)
	v_pk_mul_f32 v[34:35], v[36:37], v[34:35]
	v_pk_mul_f32 v[36:37], v[38:39], v[32:33]
	global_store_dwordx4 v[30:31], v[34:37], off nt
	v_mov_b32_e32 v32, v27
	v_mov_b32_e32 v27, v28
	v_mov_b32_e32 v33, v29
	v_pk_mul_f32 v[34:35], v[4:5], v[26:27] op_sel_hi:[0,1]
	global_load_dwordx4 v[26:29], v[8:9], off offset:1024
	v_pk_mul_f32 v[32:33], v[4:5], v[32:33] op_sel_hi:[0,1]
	s_waitcnt vmcnt(0)
	v_pk_mul_f32 v[26:27], v[26:27], v[34:35]
	v_pk_mul_f32 v[28:29], v[28:29], v[32:33]
	global_store_dwordx4 v[30:31], v[26:29], off offset:1024 nt
	s_nop 1
	v_pk_mul_f32 v[26:27], v[4:5], v[22:23] op_sel_hi:[0,1]
	v_pk_mul_f32 v[28:29], v[4:5], v[24:25] op_sel_hi:[0,1]
	global_load_dwordx4 v[22:25], v[8:9], off offset:2048
	s_waitcnt vmcnt(0)
	v_pk_mul_f32 v[22:23], v[22:23], v[28:29]
	v_pk_mul_f32 v[24:25], v[24:25], v[26:27]
	global_store_dwordx4 v[30:31], v[22:25], off offset:2048 nt
	v_lshlrev_b32_e32 v26, 16, v18
	v_and_b32_e32 v27, 0xffff0000, v18
	v_pk_mul_f32 v[22:23], v[2:3], v[4:5] op_sel_hi:[1,0]
	global_load_dwordx4 v[2:5], v[8:9], off offset:3072
	v_and_b32_e32 v25, 0xffff0000, v19
	v_lshlrev_b32_e32 v24, 16, v19
	v_lshlrev_b32_e32 v19, 16, v17
	v_lshlrev_b32_e32 v18, 16, v16
	s_waitcnt vmcnt(0)
	v_pk_mul_f32 v[2:3], v[2:3], v[22:23]
	v_pk_mul_f32 v[4:5], v[4:5], v[20:21]
	global_store_dwordx4 v[30:31], v[2:5], off offset:3072 nt
	v_and_b32_e32 v21, 0xffff0000, v17
	v_and_b32_e32 v20, 0xffff0000, v16
	v_mul_f32_e32 v2, v25, v25
	v_pk_fma_f32 v[22:23], v[24:25], v[24:25], v[2:3] op_sel_hi:[1,1,0]
	v_pk_mul_f32 v[2:3], v[20:21], v[20:21]
	v_lshlrev_b32_e32 v5, 16, v12
	v_pk_fma_f32 v[28:29], v[18:19], v[18:19], v[2:3]
	v_and_b32_e32 v3, 0xffff0000, v12
	v_mul_f32_e32 v2, v27, v27
	v_pk_fma_f32 v[30:31], v[26:27], v[26:27], v[2:3] op_sel_hi:[1,1,0]
	v_mov_b32_e32 v32, v22
	v_mov_b32_e32 v4, v30
	v_mov_b32_e32 v33, v5
	v_and_b32_e32 v17, 0xffff0000, v14
	v_mul_f32_e32 v34, v3, v3
	v_pk_add_f32 v[22:23], v[30:31], v[22:23]
	v_pk_mul_f32 v[30:31], v[4:5], v[32:33]
	v_pk_add_f32 v[28:29], v[28:29], v[28:29] op_sel:[0,1] op_sel_hi:[1,0]
	v_lshlrev_b32_e32 v16, 16, v14
	v_lshlrev_b32_e32 v14, 16, v15
	v_and_b32_e32 v15, 0xffff0000, v15
	v_mov_b32_e32 v23, v31
	v_mov_b32_e32 v29, v34
	v_mul_f32_e32 v2, v17, v17
	v_lshlrev_b32_e32 v12, 16, v13
	v_and_b32_e32 v13, 0xffff0000, v13
	v_pk_add_f32 v[22:23], v[22:23], v[28:29]
	v_pk_fma_f32 v[28:29], v[16:17], v[16:17], v[2:3] op_sel_hi:[1,1,0]
	v_mul_f32_e32 v2, v15, v15
	v_mul_f32_e32 v35, v12, v12
	v_mul_f32_e32 v36, v13, v13
	v_pk_fma_f32 v[30:31], v[14:15], v[14:15], v[2:3] op_sel_hi:[1,1,0]
	v_mov_b32_e32 v29, v35
	v_mov_b32_e32 v31, v36
	v_pk_add_f32 v[28:29], v[28:29], v[30:31]
	s_nop 0
	v_pk_add_f32 v[22:23], v[22:23], v[28:29]
	s_nop 0
	v_add_f32_e32 v2, v22, v23
	s_nop 1
	v_mov_b32_dpp v4, v2 quad_perm:[1,0,3,2] row_mask:0xf bank_mask:0xf
	v_lshl_add_u64 v[22:23], v[10:11], 0, s[6:7]
	s_waitcnt lgkmcnt(0)
	v_add_f32_e32 v2, v2, v4
	s_nop 1
	v_mov_b32_dpp v4, v2 quad_perm:[2,3,0,1] row_mask:0xf bank_mask:0xf
	s_waitcnt lgkmcnt(0)
	v_add_f32_e32 v2, v2, v4
	s_nop 1
	v_mov_b32_dpp v4, v2 row_half_mirror row_mask:0xf bank_mask:0xf
	s_waitcnt lgkmcnt(0)
	v_add_f32_e32 v2, v2, v4
	s_nop 1
	v_mov_b32_dpp v4, v2 row_mirror row_mask:0xf bank_mask:0xf
	s_waitcnt lgkmcnt(0)
	v_add_f32_e32 v2, v2, v4
	v_mov_b32_e32 v4, v2
	s_nop 1
	v_permlane16_swap_b32_e32 v2, v4
	s_waitcnt lgkmcnt(0)
	v_add_f32_e32 v2, v2, v4
	v_mov_b32_e32 v4, v2
	s_nop 1
	v_permlane32_swap_b32_e32 v2, v4
	s_waitcnt lgkmcnt(0)
	v_add_f32_e32 v2, v2, v4
	v_fmamk_f32 v2, v2, 0x3a800000, v166
	v_cmp_gt_f32_e32 vcc, s15, v2
	v_mul_f32_e32 v4, 0x4f800000, v2
	s_nop 0
	v_cndmask_b32_e32 v2, v2, v4, vcc
	v_sqrt_f32_e32 v4, v2
	s_nop 0
	v_add_u32_e32 v28, -1, v4
	v_fma_f32 v29, -v28, v4, v2
	v_cmp_ge_f32_e64 s[6:7], 0, v29
	v_add_u32_e32 v29, 1, v4
	s_nop 0
	v_cndmask_b32_e64 v28, v4, v28, s[6:7]
	v_fma_f32 v4, -v29, v4, v2
	v_cmp_lt_f32_e64 s[6:7], 0, v4
	s_nop 1
	v_cndmask_b32_e64 v4, v28, v29, s[6:7]
	v_mul_f32_e32 v28, 0x37800000, v4
	v_cndmask_b32_e32 v4, v4, v28, vcc
	v_cmp_class_f32_e32 vcc, v2, v167
	s_nop 1
	v_cndmask_b32_e32 v2, v4, v2, vcc
	v_div_scale_f32 v4, s[6:7], v2, v2, 1.0
	v_rcp_f32_e32 v28, v4
	s_add_i32 s6, s4, s16
	s_cmp_lt_i32 s6, 0x8000
	v_fma_f32 v29, -v4, v28, 1.0
	v_fmac_f32_e32 v28, v29, v28
	v_div_scale_f32 v29, vcc, 1.0, v2, 1.0
	v_mul_f32_e32 v30, v29, v28
	v_fma_f32 v31, -v4, v30, v29
	v_fmac_f32_e32 v30, v31, v28
	v_fma_f32 v4, -v4, v30, v29
	v_div_fmas_f32 v4, v4, v28, v30
	global_load_dwordx4 v[28:31], v[8:9], off
	v_div_fixup_f32 v4, v4, v2, 1.0
	v_pk_mul_f32 v[24:25], v[4:5], v[24:25] op_sel_hi:[0,1]
	v_pk_mul_f32 v[26:27], v[4:5], v[26:27] op_sel_hi:[0,1]
	v_mov_b32_e32 v2, v5
	v_pk_mul_f32 v[12:13], v[12:13], v[4:5] op_sel_hi:[1,0]
	s_waitcnt vmcnt(0)
	v_pk_mul_f32 v[26:27], v[28:29], v[26:27]
	v_pk_mul_f32 v[28:29], v[30:31], v[24:25]
	global_store_dwordx4 v[22:23], v[26:29], off nt
	v_mov_b32_e32 v24, v19
	v_mov_b32_e32 v19, v20
	v_mov_b32_e32 v25, v21
	v_pk_mul_f32 v[26:27], v[4:5], v[18:19] op_sel_hi:[0,1]
	global_load_dwordx4 v[18:21], v[8:9], off offset:1024
	v_pk_mul_f32 v[24:25], v[4:5], v[24:25] op_sel_hi:[0,1]
	s_waitcnt vmcnt(0)
	v_pk_mul_f32 v[18:19], v[18:19], v[26:27]
	v_pk_mul_f32 v[20:21], v[20:21], v[24:25]
	global_store_dwordx4 v[22:23], v[18:21], off offset:1024 nt
	s_nop 1
	v_pk_mul_f32 v[18:19], v[4:5], v[14:15] op_sel_hi:[0,1]
	v_pk_mul_f32 v[20:21], v[4:5], v[16:17] op_sel_hi:[0,1]
	global_load_dwordx4 v[14:17], v[8:9], off offset:2048
	s_waitcnt vmcnt(0)
	v_pk_mul_f32 v[14:15], v[14:15], v[20:21]
	v_pk_mul_f32 v[16:17], v[16:17], v[18:19]
	global_store_dwordx4 v[22:23], v[14:17], off offset:2048 nt
	s_nop 1
	v_pk_mul_f32 v[14:15], v[2:3], v[4:5] op_sel_hi:[1,0]
	global_load_dwordx4 v[2:5], v[8:9], off offset:3072
	s_waitcnt vmcnt(0)
	v_pk_mul_f32 v[2:3], v[2:3], v[14:15]
	v_pk_mul_f32 v[4:5], v[4:5], v[12:13]
	global_store_dwordx4 v[22:23], v[2:5], off offset:3072 nt
	s_cbranch_scc1 .LBB0_129

.Lfrkvq_issued:
	s_waitcnt vmcnt(0)
	s_mov_b64 s[22:23], s[2:3]
	s_waitcnt lgkmcnt(0)
	v_mov_b64_e32 v[6:7], s[8:9]
	v_cmp_ge_i64_e32 vcc, s[22:23], v[6:7]
	s_mov_b64 s[26:27], -1
	s_cbranch_vccnz .Lfrkvq_done
	v_pk_add_f32 v[16:17], v[16:17], v[20:21]
	v_pk_add_f32 v[14:15], v[14:15], v[18:19]
	v_cmp_lt_i32_e32 vcc, v172, v171
	v_add_f32_e32 v6, v14, v15
	v_add_f32_e32 v7, v16, v17
	v_add_f32_e32 v6, v6, v7
	s_nop 1
	v_mov_b32_dpp v7, v6 quad_perm:[1,0,3,2] row_mask:0xf bank_mask:0xf
	s_and_saveexec_b64 s[26:27], s[6:7]
	s_waitcnt lgkmcnt(0)
	v_add_f32_e32 v6, v6, v7
	v_fmamk_f32 v6, v6, 0x3a800000, v166
	v_rsq_f32_e32 v6, v6
	ds_write_b32 v5, v6
	s_or_b64 exec, exec, s[26:27]
	s_add_u32 s22, s22, s14
	s_addc_u32 s23, s23, s55
	s_waitcnt lgkmcnt(0)
	v_mov_b64_e32 v[6:7], s[8:9]
	v_cmp_ge_i64_e32 vcc, s[22:23], v[6:7]
	s_mov_b64 s[26:27], -1
	s_cbranch_vccnz .Lfrkvq_done
	v_pk_add_f32 v[24:25], v[24:25], v[28:29]
	v_pk_add_f32 v[22:23], v[22:23], v[26:27]
	v_cmp_lt_i32_e32 vcc, v172, v171
	v_add_f32_e32 v6, v22, v23
	v_add_f32_e32 v7, v24, v25
	v_add_f32_e32 v6, v6, v7
	s_nop 1
	v_mov_b32_dpp v7, v6 quad_perm:[1,0,3,2] row_mask:0xf bank_mask:0xf
	s_and_saveexec_b64 s[26:27], s[6:7]
	s_waitcnt lgkmcnt(0)
	v_add_f32_e32 v6, v6, v7
	v_fmamk_f32 v6, v6, 0x3a800000, v166
	v_rsq_f32_e32 v6, v6
	ds_write_b32 v5, v6 offset:1024
	s_or_b64 exec, exec, s[26:27]
	s_add_u32 s22, s22, s14
	s_addc_u32 s23, s23, s55
	s_waitcnt lgkmcnt(0)
	v_mov_b64_e32 v[6:7], s[8:9]
	v_cmp_ge_i64_e32 vcc, s[22:23], v[6:7]
	s_mov_b64 s[26:27], -1
	s_cbranch_vccnz .Lfrkvq_done
	v_pk_add_f32 v[32:33], v[32:33], v[36:37]
	v_pk_add_f32 v[30:31], v[30:31], v[34:35]
	v_cmp_lt_i32_e32 vcc, v172, v171
	v_add_f32_e32 v6, v30, v31
	v_add_f32_e32 v7, v32, v33
	v_add_f32_e32 v6, v6, v7
	s_nop 1
	v_mov_b32_dpp v7, v6 quad_perm:[1,0,3,2] row_mask:0xf bank_mask:0xf
	s_and_saveexec_b64 s[26:27], s[6:7]
	s_waitcnt lgkmcnt(0)
	v_add_f32_e32 v6, v6, v7
	v_fmamk_f32 v6, v6, 0x3a800000, v166
	v_rsq_f32_e32 v6, v6
	ds_write_b32 v5, v6 offset:2048
	s_or_b64 exec, exec, s[26:27]
	s_add_u32 s22, s22, s14
	s_addc_u32 s23, s23, s55

.Lfrup_issued:
	s_waitcnt vmcnt(0)
	s_mov_b64 s[8:9], s[2:3]
	v_cmp_gt_i64_e32 vcc, s[8:9], v[136:137]
	s_mov_b64 s[12:13], -1
	s_cbranch_vccnz .Lfrup_done
	v_pk_add_f32 v[16:17], v[16:17], v[20:21]
	v_pk_add_f32 v[14:15], v[14:15], v[18:19]
	v_cmp_lt_i32_e32 vcc, v172, v171
	v_add_f32_e32 v6, v14, v15
	v_add_f32_e32 v7, v16, v17
	v_add_f32_e32 v6, v6, v7
	s_nop 1
	v_mov_b32_dpp v7, v6 quad_perm:[1,0,3,2] row_mask:0xf bank_mask:0xf
	s_and_saveexec_b64 s[12:13], s[6:7]
	s_waitcnt lgkmcnt(0)
	v_add_f32_e32 v6, v6, v7
	v_fmamk_f32 v6, v6, 0x3a800000, v166
	v_rsq_f32_e32 v6, v6
	ds_write_b32 v5, v6
	s_or_b64 exec, exec, s[12:13]
	s_add_u32 s8, s8, s14
	s_addc_u32 s9, s9, s55
	v_cmp_gt_i64_e32 vcc, s[8:9], v[136:137]
	s_mov_b64 s[12:13], -1
	s_cbranch_vccnz .Lfrup_done
	v_pk_add_f32 v[24:25], v[24:25], v[28:29]
	v_pk_add_f32 v[22:23], v[22:23], v[26:27]
	v_cmp_lt_i32_e32 vcc, v172, v171
	v_add_f32_e32 v6, v22, v23
	v_add_f32_e32 v7, v24, v25
	v_add_f32_e32 v6, v6, v7
	s_nop 1
	v_mov_b32_dpp v7, v6 quad_perm:[1,0,3,2] row_mask:0xf bank_mask:0xf
	s_and_saveexec_b64 s[12:13], s[6:7]
	s_waitcnt lgkmcnt(0)
	v_add_f32_e32 v6, v6, v7
	v_fmamk_f32 v6, v6, 0x3a800000, v166
	v_rsq_f32_e32 v6, v6
	ds_write_b32 v5, v6 offset:1024
	s_or_b64 exec, exec, s[12:13]
	s_add_u32 s8, s8, s14
	s_addc_u32 s9, s9, s55
	v_cmp_gt_i64_e32 vcc, s[8:9], v[136:137]
	s_mov_b64 s[12:13], -1
	s_cbranch_vccnz .Lfrup_done
	v_pk_add_f32 v[32:33], v[32:33], v[36:37]
	v_pk_add_f32 v[30:31], v[30:31], v[34:35]
	v_cmp_lt_i32_e32 vcc, v172, v171
	v_add_f32_e32 v6, v30, v31
	v_add_f32_e32 v7, v32, v33
	v_add_f32_e32 v6, v6, v7
	s_nop 1
	v_mov_b32_dpp v7, v6 quad_perm:[1,0,3,2] row_mask:0xf bank_mask:0xf
	s_and_saveexec_b64 s[12:13], s[6:7]
	s_waitcnt lgkmcnt(0)
	v_add_f32_e32 v6, v6, v7
	v_fmamk_f32 v6, v6, 0x3a800000, v166
	v_rsq_f32_e32 v6, v6
	ds_write_b32 v5, v6 offset:2048
	s_or_b64 exec, exec, s[12:13]
	s_add_u32 s8, s8, s14
	s_addc_u32 s9, s9, s55
	v_cmp_gt_i64_e32 vcc, s[8:9], v[136:137]
	s_mov_b64 s[12:13], -1
	s_cbranch_vccnz .Lfrup_done
	v_pk_add_f32 v[40:41], v[40:41], v[44:45]
	v_pk_add_f32 v[38:39], v[38:39], v[42:43]
	v_cmp_lt_i32_e32 vcc, v172, v171
	v_add_f32_e32 v6, v38, v39
	v_add_f32_e32 v7, v40, v41
	v_add_f32_e32 v6, v6, v7
	s_nop 1
	v_mov_b32_dpp v7, v6 quad_perm:[1,0,3,2] row_mask:0xf bank_mask:0xf
	s_and_saveexec_b64 s[12:13], s[6:7]
	s_waitcnt lgkmcnt(0)
	v_add_f32_e32 v6, v6, v7
	v_fmamk_f32 v6, v6, 0x3a800000, v166
	v_rsq_f32_e32 v6, v6
	ds_write_b32 v5, v6 offset:3072
	s_or_b64 exec, exec, s[12:13]
	s_add_u32 s8, s8, s14
	s_addc_u32 s9, s9, s55
	v_cmp_gt_i64_e32 vcc, s[8:9], v[136:137]
	s_mov_b64 s[12:13], -1
	s_cbranch_vccnz .Lfrup_done
	v_pk_add_f32 v[48:49], v[48:49], v[52:53]
	v_pk_add_f32 v[46:47], v[46:47], v[50:51]
	v_cmp_lt_i32_e32 vcc, v172, v171
	v_add_f32_e32 v6, v46, v47
	v_add_f32_e32 v7, v48, v49
	v_add_f32_e32 v6, v6, v7
	s_nop 1
	v_mov_b32_dpp v7, v6 quad_perm:[1,0,3,2] row_mask:0xf bank_mask:0xf
	s_and_saveexec_b64 s[12:13], s[6:7]
	s_waitcnt lgkmcnt(0)
	v_add_f32_e32 v6, v6, v7
	v_fmamk_f32 v6, v6, 0x3a800000, v166
	v_rsq_f32_e32 v6, v6
	ds_write_b32 v5, v6 offset:4096
	s_or_b64 exec, exec, s[12:13]
	s_add_u32 s8, s8, s14
	s_addc_u32 s9, s9, s55
	v_cmp_gt_i64_e32 vcc, s[8:9], v[136:137]
	s_mov_b64 s[12:13], -1
	s_cbranch_vccnz .Lfrup_done
	v_pk_add_f32 v[56:57], v[56:57], v[60:61]
	v_pk_add_f32 v[54:55], v[54:55], v[58:59]
	v_cmp_lt_i32_e32 vcc, v172, v171
	v_add_f32_e32 v6, v54, v55
	v_add_f32_e32 v7, v56, v57
	v_add_f32_e32 v6, v6, v7
	s_nop 1
	v_mov_b32_dpp v7, v6 quad_perm:[1,0,3,2] row_mask:0xf bank_mask:0xf
	s_and_saveexec_b64 s[12:13], s[6:7]
	s_waitcnt lgkmcnt(0)
	v_add_f32_e32 v6, v6, v7
	v_fmamk_f32 v6, v6, 0x3a800000, v166
	v_rsq_f32_e32 v6, v6
	ds_write_b32 v5, v6 offset:5120
	s_or_b64 exec, exec, s[12:13]
	s_add_u32 s8, s8, s14
	s_addc_u32 s9, s9, s55
	v_cmp_gt_i64_e32 vcc, s[8:9], v[136:137]
	s_mov_b64 s[12:13], -1
	s_cbranch_vccnz .Lfrup_done
	v_pk_add_f32 v[64:65], v[64:65], v[68:69]
	v_pk_add_f32 v[62:63], v[62:63], v[66:67]
	v_cmp_lt_i32_e32 vcc, v172, v171
	v_add_f32_e32 v6, v62, v63
	v_add_f32_e32 v7, v64, v65
	v_add_f32_e32 v6, v6, v7
	s_nop 1
	v_mov_b32_dpp v7, v6 quad_perm:[1,0,3,2] row_mask:0xf bank_mask:0xf
	s_and_saveexec_b64 s[12:13], s[6:7]
	s_waitcnt lgkmcnt(0)
	v_add_f32_e32 v6, v6, v7
	v_fmamk_f32 v6, v6, 0x3a800000, v166
	v_rsq_f32_e32 v6, v6
	ds_write_b32 v5, v6 offset:6144
	s_or_b64 exec, exec, s[12:13]
	s_add_u32 s8, s8, s14
	s_addc_u32 s9, s9, s55
	v_cmp_gt_i64_e32 vcc, s[8:9], v[136:137]
	s_mov_b64 s[12:13], -1
	s_cbranch_vccnz .Lfrup_done
	v_pk_add_f32 v[72:73], v[72:73], v[76:77]
	v_pk_add_f32 v[70:71], v[70:71], v[74:75]
	v_cmp_lt_i32_e32 vcc, v172, v171
	v_add_f32_e32 v6, v70, v71
	v_add_f32_e32 v7, v72, v73
	v_add_f32_e32 v6, v6, v7
	s_nop 1
	v_mov_b32_dpp v7, v6 quad_perm:[1,0,3,2] row_mask:0xf bank_mask:0xf
	s_and_saveexec_b64 s[12:13], s[6:7]
	s_waitcnt lgkmcnt(0)
	v_add_f32_e32 v6, v6, v7
	v_fmamk_f32 v6, v6, 0x3a800000, v166
	v_rsq_f32_e32 v6, v6
	ds_write_b32 v5, v6 offset:7168
	s_or_b64 exec, exec, s[12:13]
	s_add_u32 s8, s8, s14
	s_addc_u32 s9, s9, s55
	v_cmp_gt_i64_e32 vcc, s[8:9], v[136:137]
	s_mov_b64 s[12:13], -1
	s_cbranch_vccnz .Lfrup_done
	v_pk_add_f32 v[80:81], v[80:81], v[84:85]
	v_pk_add_f32 v[78:79], v[78:79], v[82:83]
	v_cmp_lt_i32_e32 vcc, v172, v171
	v_add_f32_e32 v6, v78, v79
	v_add_f32_e32 v7, v80, v81
	v_add_f32_e32 v6, v6, v7
	s_nop 1
	v_mov_b32_dpp v7, v6 quad_perm:[1,0,3,2] row_mask:0xf bank_mask:0xf
	s_and_saveexec_b64 s[12:13], s[6:7]
	s_waitcnt lgkmcnt(0)
	v_add_f32_e32 v6, v6, v7
	v_fmamk_f32 v6, v6, 0x3a800000, v166
	v_rsq_f32_e32 v6, v6
	ds_write_b32 v5, v6 offset:8192
	s_or_b64 exec, exec, s[12:13]
	s_add_u32 s8, s8, s14
	s_addc_u32 s9, s9, s55
	v_cmp_gt_i64_e32 vcc, s[8:9], v[136:137]
	s_mov_b64 s[12:13], -1
	s_cbranch_vccnz .Lfrup_done
	v_pk_add_f32 v[88:89], v[88:89], v[92:93]
	v_pk_add_f32 v[86:87], v[86:87], v[90:91]
	v_cmp_lt_i32_e32 vcc, v172, v171
	v_add_f32_e32 v6, v86, v87
	v_add_f32_e32 v7, v88, v89
	v_add_f32_e32 v6, v6, v7
	s_nop 1
	v_mov_b32_dpp v7, v6 quad_perm:[1,0,3,2] row_mask:0xf bank_mask:0xf
	s_and_saveexec_b64 s[12:13], s[6:7]
	s_waitcnt lgkmcnt(0)
	v_add_f32_e32 v6, v6, v7
	v_fmamk_f32 v6, v6, 0x3a800000, v166
	v_rsq_f32_e32 v6, v6
	ds_write_b32 v5, v6 offset:9216
	s_or_b64 exec, exec, s[12:13]
	s_add_u32 s8, s8, s14
	s_addc_u32 s9, s9, s55
	v_cmp_gt_i64_e32 vcc, s[8:9], v[136:137]
	s_mov_b64 s[12:13], -1
	s_cbranch_vccnz .Lfrup_done
	v_pk_add_f32 v[96:97], v[96:97], v[100:101]
	v_pk_add_f32 v[94:95], v[94:95], v[98:99]
	v_cmp_lt_i32_e32 vcc, v172, v171
	v_add_f32_e32 v6, v94, v95
	v_add_f32_e32 v7, v96, v97
	v_add_f32_e32 v6, v6, v7
	s_nop 1
	v_mov_b32_dpp v7, v6 quad_perm:[1,0,3,2] row_mask:0xf bank_mask:0xf
	s_and_saveexec_b64 s[12:13], s[6:7]
	s_waitcnt lgkmcnt(0)
	v_add_f32_e32 v6, v6, v7
	v_fmamk_f32 v6, v6, 0x3a800000, v166
	v_rsq_f32_e32 v6, v6
	ds_write_b32 v5, v6 offset:10240
	s_or_b64 exec, exec, s[12:13]
	s_add_u32 s8, s8, s14
	s_addc_u32 s9, s9, s55

.LBB0_321:
	v_cmp_lt_i32_e32 vcc, v176, v171
	v_lshl_add_u32 v154, s21, 8, v131
	v_lshl_or_b32 v152, s19, 8, v160
	v_cndmask_b32_e32 v155, v170, v176, vcc
	v_cmp_lt_i32_e32 vcc, v177, v171
	v_lshlrev_b32_e32 v164, 2, v155
	v_ashrrev_i32_e32 v153, 31, v152
	v_cndmask_b32_e32 v155, v170, v177, vcc
	v_lshlrev_b32_e32 v162, 2, v155
	v_ashrrev_i32_e32 v155, 31, v154
	v_lshlrev_b64 v[156:157], 11, v[154:155]
	v_lshl_add_u64 v[156:157], s[78:79], 0, v[156:157]
	v_lshl_add_u64 v[156:157], v[152:153], 1, v[156:157]
	s_lshl_b32 vcc_lo, s19, 2
	s_ashr_i32 vcc_hi, vcc_lo, 31
	s_waitcnt vmcnt(15)
	v_lshlrev_b32_e32 v182, 16, v186
	v_and_b32_e32 v183, 0xffff0000, v186
	v_lshlrev_b32_e32 v178, 16, v187
	v_and_b32_e32 v179, 0xffff0000, v187
	v_lshlrev_b32_e32 v184, 16, v188
	v_and_b32_e32 v185, 0xffff0000, v188
	v_lshlrev_b32_e32 v180, 16, v189
	v_and_b32_e32 v181, 0xffff0000, v189
	v_pk_add_f32 v[128:129], v[128:129], v[178:179]
	v_pk_add_f32 v[126:127], v[126:127], v[182:183]
	v_pk_add_f32 v[178:179], v[124:125], v[180:181]
	v_pk_add_f32 v[180:181], v[122:123], v[184:185]
	v_cvt_pk_bf16_f32 v122, v126, v127
	v_cvt_pk_bf16_f32 v123, v128, v129
	v_cvt_pk_bf16_f32 v124, v180, v181
	v_cvt_pk_bf16_f32 v125, v178, v179
	global_store_dwordx4 v[156:157], v[122:125], off
	s_nop 1
	v_mul_f32_e32 v122, v127, v127
	v_mul_f32_e32 v123, v129, v129
	v_fmac_f32_e32 v122, v126, v126
	v_fmac_f32_e32 v123, v128, v128
	v_add_f32_e32 v122, v122, v123
	v_mul_f32_e32 v123, v181, v181
	v_fmac_f32_e32 v123, v180, v180
	v_add_f32_e32 v122, v123, v122
	v_mul_f32_e32 v123, v179, v179
	v_fmac_f32_e32 v123, v178, v178
	v_add_f32_e32 v165, v123, v122
	s_waitcnt vmcnt(15)
	v_lshlrev_b32_e32 v126, 16, v190
	v_and_b32_e32 v127, 0xffff0000, v190
	v_lshlrev_b32_e32 v122, 16, v191
	v_and_b32_e32 v123, 0xffff0000, v191
	v_lshlrev_b32_e32 v128, 16, v192
	v_and_b32_e32 v129, 0xffff0000, v192
	v_lshlrev_b32_e32 v124, 16, v193
	v_and_b32_e32 v125, 0xffff0000, v193
	v_pk_add_f32 v[120:121], v[120:121], v[122:123]
	v_pk_add_f32 v[118:119], v[118:119], v[126:127]
	v_pk_add_f32 v[122:123], v[116:117], v[124:125]
	v_pk_add_f32 v[124:125], v[114:115], v[128:129]
	v_cvt_pk_bf16_f32 v114, v118, v119
	v_cvt_pk_bf16_f32 v115, v120, v121
	v_cvt_pk_bf16_f32 v116, v124, v125
	v_cvt_pk_bf16_f32 v117, v122, v123
	global_store_dwordx4 v[156:157], v[114:117], off offset:256
	s_nop 1
	v_mul_f32_e32 v114, v119, v119
	v_mul_f32_e32 v115, v121, v121
	v_fmac_f32_e32 v114, v118, v118
	v_fmac_f32_e32 v115, v120, v120
	v_add_f32_e32 v114, v114, v115
	v_mul_f32_e32 v115, v125, v125
	v_fmac_f32_e32 v115, v124, v124
	v_add_f32_e32 v114, v115, v114
	v_mul_f32_e32 v115, v123, v123
	v_fmac_f32_e32 v115, v122, v122
	v_add_f32_e32 v114, v115, v114
	v_add_f32_e32 v114, v165, v114
	v_mov_b32_e32 v115, v114
	s_nop 1
	v_permlane16_swap_b32_e32 v114, v115
	v_add_f32_e32 v114, v114, v115
	v_mov_b32_e32 v115, v114
	s_nop 1
	v_permlane32_swap_b32_e32 v114, v115
	s_and_saveexec_b64 s[12:13], s[6:7]
	s_cbranch_execz .LBB0_323
	s_waitcnt lgkmcnt(0)
	v_add_f32_e32 v116, v114, v115
	v_lshlrev_b64 v[114:115], 6, v[154:155]
	v_lshl_add_u64 v[114:115], s[82:83], 0, v[114:115]
	v_lshl_add_u64 v[114:115], vcc, 2, v[114:115]
	s_lshl_b32 s60, s53, 2
	v_lshl_add_u64 v[114:115], v[114:115], 0, s[60:61]
	global_store_dword v[114:115], v116, off
.LBB0_323:
	s_or_b64 exec, exec, s[12:13]
	v_or_b32_e32 v114, 16, v154
	s_waitcnt lgkmcnt(0)
	v_ashrrev_i32_e32 v115, 31, v114
	v_lshlrev_b64 v[116:117], 11, v[114:115]
	v_lshl_add_u64 v[116:117], s[78:79], 0, v[116:117]
	v_lshl_add_u64 v[120:121], v[152:153], 1, v[116:117]
	s_waitcnt vmcnt(16)
	v_lshlrev_b32_e32 v122, 16, v194
	v_and_b32_e32 v123, 0xffff0000, v194
	v_lshlrev_b32_e32 v116, 16, v195
	v_and_b32_e32 v117, 0xffff0000, v195
	v_lshlrev_b32_e32 v124, 16, v196
	v_and_b32_e32 v125, 0xffff0000, v196
	v_lshlrev_b32_e32 v118, 16, v197
	v_and_b32_e32 v119, 0xffff0000, v197
	v_pk_add_f32 v[112:113], v[112:113], v[116:117]
	v_pk_add_f32 v[110:111], v[110:111], v[122:123]
	v_pk_add_f32 v[116:117], v[108:109], v[118:119]
	v_pk_add_f32 v[118:119], v[106:107], v[124:125]
	v_cvt_pk_bf16_f32 v106, v110, v111
	v_cvt_pk_bf16_f32 v107, v112, v113
	v_cvt_pk_bf16_f32 v108, v118, v119
	v_cvt_pk_bf16_f32 v109, v116, v117
	global_store_dwordx4 v[120:121], v[106:109], off
	s_nop 1
	v_mul_f32_e32 v106, v111, v111
	v_mul_f32_e32 v107, v113, v113
	v_fmac_f32_e32 v106, v110, v110
	v_fmac_f32_e32 v107, v112, v112
	v_add_f32_e32 v106, v106, v107
	v_mul_f32_e32 v107, v119, v119
	v_fmac_f32_e32 v107, v118, v118
	v_add_f32_e32 v106, v107, v106
	v_mul_f32_e32 v107, v117, v117
	v_fmac_f32_e32 v107, v116, v116
	v_add_f32_e32 v116, v107, v106
	s_waitcnt vmcnt(16)
	v_lshlrev_b32_e32 v110, 16, v198
	v_and_b32_e32 v111, 0xffff0000, v198
	v_lshlrev_b32_e32 v106, 16, v199
	v_and_b32_e32 v107, 0xffff0000, v199
	v_lshlrev_b32_e32 v112, 16, v200
	v_and_b32_e32 v113, 0xffff0000, v200
	v_lshlrev_b32_e32 v108, 16, v201
	v_and_b32_e32 v109, 0xffff0000, v201
	v_pk_add_f32 v[104:105], v[104:105], v[106:107]
	v_pk_add_f32 v[102:103], v[102:103], v[110:111]
	v_pk_add_f32 v[106:107], v[100:101], v[108:109]
	v_pk_add_f32 v[108:109], v[98:99], v[112:113]
	v_cvt_pk_bf16_f32 v98, v102, v103
	v_cvt_pk_bf16_f32 v99, v104, v105
	v_cvt_pk_bf16_f32 v100, v108, v109
	v_cvt_pk_bf16_f32 v101, v106, v107
	global_store_dwordx4 v[120:121], v[98:101], off offset:256
	s_nop 1
	v_mul_f32_e32 v98, v103, v103
	v_mul_f32_e32 v99, v105, v105
	v_fmac_f32_e32 v98, v102, v102
	v_fmac_f32_e32 v99, v104, v104
	v_add_f32_e32 v98, v98, v99
	v_mul_f32_e32 v99, v109, v109
	v_fmac_f32_e32 v99, v108, v108
	v_add_f32_e32 v98, v99, v98
	v_mul_f32_e32 v99, v107, v107
	v_fmac_f32_e32 v99, v106, v106
	v_add_f32_e32 v98, v99, v98
	v_add_f32_e32 v98, v116, v98
	v_mov_b32_e32 v99, v98
	s_nop 1
	v_permlane16_swap_b32_e32 v98, v99
	v_add_f32_e32 v98, v98, v99
	v_mov_b32_e32 v99, v98
	s_nop 1
	v_permlane32_swap_b32_e32 v98, v99
	s_and_saveexec_b64 s[12:13], s[6:7]
	s_cbranch_execz .LBB0_325
	s_waitcnt lgkmcnt(0)
	v_add_f32_e32 v100, v98, v99
	v_lshlrev_b64 v[98:99], 6, v[114:115]
	v_lshl_add_u64 v[98:99], s[82:83], 0, v[98:99]
	v_lshl_add_u64 v[98:99], vcc, 2, v[98:99]
	s_lshl_b32 s60, s53, 2
	v_lshl_add_u64 v[98:99], v[98:99], 0, s[60:61]
	global_store_dword v[98:99], v100, off
.LBB0_325:
	s_or_b64 exec, exec, s[12:13]
	v_or_b32_e32 v98, 32, v154
	s_waitcnt lgkmcnt(0)
	v_ashrrev_i32_e32 v99, 31, v98
	v_lshlrev_b64 v[100:101], 11, v[98:99]
	v_lshl_add_u64 v[100:101], s[78:79], 0, v[100:101]
	v_lshl_add_u64 v[104:105], v[152:153], 1, v[100:101]
	s_waitcnt vmcnt(17)
	v_lshlrev_b32_e32 v106, 16, v202
	v_and_b32_e32 v107, 0xffff0000, v202
	v_lshlrev_b32_e32 v100, 16, v203
	v_and_b32_e32 v101, 0xffff0000, v203
	v_lshlrev_b32_e32 v108, 16, v204
	v_and_b32_e32 v109, 0xffff0000, v204
	v_lshlrev_b32_e32 v102, 16, v205
	v_and_b32_e32 v103, 0xffff0000, v205
	v_pk_add_f32 v[96:97], v[96:97], v[100:101]
	v_pk_add_f32 v[94:95], v[94:95], v[106:107]
	v_pk_add_f32 v[100:101], v[92:93], v[102:103]
	v_pk_add_f32 v[102:103], v[90:91], v[108:109]
	v_cvt_pk_bf16_f32 v90, v94, v95
	v_cvt_pk_bf16_f32 v91, v96, v97
	v_cvt_pk_bf16_f32 v92, v102, v103
	v_cvt_pk_bf16_f32 v93, v100, v101
	global_store_dwordx4 v[104:105], v[90:93], off
	s_nop 1
	v_mul_f32_e32 v90, v95, v95
	v_mul_f32_e32 v91, v97, v97
	v_fmac_f32_e32 v90, v94, v94
	v_fmac_f32_e32 v91, v96, v96
	v_add_f32_e32 v90, v90, v91
	v_mul_f32_e32 v91, v103, v103
	v_fmac_f32_e32 v91, v102, v102
	v_add_f32_e32 v90, v91, v90
	v_mul_f32_e32 v91, v101, v101
	v_fmac_f32_e32 v91, v100, v100
	v_add_f32_e32 v100, v91, v90
	s_waitcnt vmcnt(17)
	v_lshlrev_b32_e32 v94, 16, v206
	v_and_b32_e32 v95, 0xffff0000, v206
	v_lshlrev_b32_e32 v90, 16, v207
	v_and_b32_e32 v91, 0xffff0000, v207
	v_lshlrev_b32_e32 v96, 16, v208
	v_and_b32_e32 v97, 0xffff0000, v208
	v_lshlrev_b32_e32 v92, 16, v209
	v_and_b32_e32 v93, 0xffff0000, v209
	v_pk_add_f32 v[88:89], v[88:89], v[90:91]
	v_pk_add_f32 v[86:87], v[86:87], v[94:95]
	v_pk_add_f32 v[90:91], v[84:85], v[92:93]
	v_pk_add_f32 v[92:93], v[82:83], v[96:97]
	v_cvt_pk_bf16_f32 v82, v86, v87
	v_cvt_pk_bf16_f32 v83, v88, v89
	v_cvt_pk_bf16_f32 v84, v92, v93
	v_cvt_pk_bf16_f32 v85, v90, v91
	global_store_dwordx4 v[104:105], v[82:85], off offset:256
	s_nop 1
	v_mul_f32_e32 v82, v87, v87
	v_mul_f32_e32 v83, v89, v89
	v_fmac_f32_e32 v82, v86, v86
	v_fmac_f32_e32 v83, v88, v88
	v_add_f32_e32 v82, v82, v83
	v_mul_f32_e32 v83, v93, v93
	v_fmac_f32_e32 v83, v92, v92
	v_add_f32_e32 v82, v83, v82
	v_mul_f32_e32 v83, v91, v91
	v_fmac_f32_e32 v83, v90, v90
	v_add_f32_e32 v82, v83, v82
	v_add_f32_e32 v82, v100, v82
	v_mov_b32_e32 v83, v82
	s_nop 1
	v_permlane16_swap_b32_e32 v82, v83
	v_add_f32_e32 v82, v82, v83
	v_mov_b32_e32 v83, v82
	s_nop 1
	v_permlane32_swap_b32_e32 v82, v83
	s_and_saveexec_b64 s[12:13], s[6:7]
	s_cbranch_execz .LBB0_327
	s_waitcnt lgkmcnt(0)
	v_add_f32_e32 v84, v82, v83
	v_lshlrev_b64 v[82:83], 6, v[98:99]
	v_lshl_add_u64 v[82:83], s[82:83], 0, v[82:83]
	v_lshl_add_u64 v[82:83], vcc, 2, v[82:83]
	s_lshl_b32 s60, s53, 2
	v_lshl_add_u64 v[82:83], v[82:83], 0, s[60:61]
	global_store_dword v[82:83], v84, off
.LBB0_327:
	s_or_b64 exec, exec, s[12:13]
	v_or_b32_e32 v82, 48, v154
	s_waitcnt lgkmcnt(0)
	v_ashrrev_i32_e32 v83, 31, v82
	v_lshlrev_b64 v[84:85], 11, v[82:83]
	v_lshl_add_u64 v[84:85], s[78:79], 0, v[84:85]
	v_lshl_add_u64 v[88:89], v[152:153], 1, v[84:85]
	s_waitcnt vmcnt(18)
	v_lshlrev_b32_e32 v90, 16, v210
	v_and_b32_e32 v91, 0xffff0000, v210
	v_lshlrev_b32_e32 v84, 16, v211
	v_and_b32_e32 v85, 0xffff0000, v211
	v_lshlrev_b32_e32 v92, 16, v212
	v_and_b32_e32 v93, 0xffff0000, v212
	v_lshlrev_b32_e32 v86, 16, v213
	v_and_b32_e32 v87, 0xffff0000, v213
	v_pk_add_f32 v[80:81], v[80:81], v[84:85]
	v_pk_add_f32 v[78:79], v[78:79], v[90:91]
	v_pk_add_f32 v[84:85], v[76:77], v[86:87]
	v_pk_add_f32 v[86:87], v[74:75], v[92:93]
	v_cvt_pk_bf16_f32 v74, v78, v79
	v_cvt_pk_bf16_f32 v75, v80, v81
	v_cvt_pk_bf16_f32 v76, v86, v87
	v_cvt_pk_bf16_f32 v77, v84, v85
	global_store_dwordx4 v[88:89], v[74:77], off
	s_nop 1
	v_mul_f32_e32 v74, v79, v79
	v_mul_f32_e32 v75, v81, v81
	v_fmac_f32_e32 v74, v78, v78
	v_fmac_f32_e32 v75, v80, v80
	v_add_f32_e32 v74, v74, v75
	v_mul_f32_e32 v75, v87, v87
	v_fmac_f32_e32 v75, v86, v86
	v_add_f32_e32 v74, v75, v74
	v_mul_f32_e32 v75, v85, v85
	v_fmac_f32_e32 v75, v84, v84
	v_add_f32_e32 v84, v75, v74
	s_waitcnt vmcnt(18)
	v_lshlrev_b32_e32 v78, 16, v214
	v_and_b32_e32 v79, 0xffff0000, v214
	v_lshlrev_b32_e32 v74, 16, v215
	v_and_b32_e32 v75, 0xffff0000, v215
	v_lshlrev_b32_e32 v80, 16, v216
	v_and_b32_e32 v81, 0xffff0000, v216
	v_lshlrev_b32_e32 v76, 16, v217
	v_and_b32_e32 v77, 0xffff0000, v217
	v_pk_add_f32 v[72:73], v[72:73], v[74:75]
	v_pk_add_f32 v[70:71], v[70:71], v[78:79]
	v_pk_add_f32 v[74:75], v[68:69], v[76:77]
	v_pk_add_f32 v[76:77], v[66:67], v[80:81]
	v_cvt_pk_bf16_f32 v66, v70, v71
	v_cvt_pk_bf16_f32 v67, v72, v73
	v_cvt_pk_bf16_f32 v68, v76, v77
	v_cvt_pk_bf16_f32 v69, v74, v75
	global_store_dwordx4 v[88:89], v[66:69], off offset:256
	s_nop 1
	v_mul_f32_e32 v66, v71, v71
	v_mul_f32_e32 v67, v73, v73
	v_fmac_f32_e32 v66, v70, v70
	v_fmac_f32_e32 v67, v72, v72
	v_add_f32_e32 v66, v66, v67
	v_mul_f32_e32 v67, v77, v77
	v_fmac_f32_e32 v67, v76, v76
	v_add_f32_e32 v66, v67, v66
	v_mul_f32_e32 v67, v75, v75
	v_fmac_f32_e32 v67, v74, v74
	v_add_f32_e32 v66, v67, v66
	v_add_f32_e32 v66, v84, v66
	v_mov_b32_e32 v67, v66
	s_nop 1
	v_permlane16_swap_b32_e32 v66, v67
	v_add_f32_e32 v66, v66, v67
	v_mov_b32_e32 v67, v66
	s_nop 1
	v_permlane32_swap_b32_e32 v66, v67
	s_and_saveexec_b64 s[12:13], s[6:7]
	s_cbranch_execz .LBB0_329
	s_waitcnt lgkmcnt(0)
	v_add_f32_e32 v68, v66, v67
	v_lshlrev_b64 v[66:67], 6, v[82:83]
	v_lshl_add_u64 v[66:67], s[82:83], 0, v[66:67]
	v_lshl_add_u64 v[66:67], vcc, 2, v[66:67]
	s_lshl_b32 s60, s53, 2
	v_lshl_add_u64 v[66:67], v[66:67], 0, s[60:61]
	global_store_dword v[66:67], v68, off
.LBB0_329:
	s_or_b64 exec, exec, s[12:13]
	v_add_u32_e32 v66, 0x80, v154
	s_waitcnt lgkmcnt(0)
	v_ashrrev_i32_e32 v67, 31, v66
	v_lshlrev_b64 v[68:69], 11, v[66:67]
	v_lshl_add_u64 v[68:69], s[78:79], 0, v[68:69]
	v_lshl_add_u64 v[72:73], v[152:153], 1, v[68:69]
	s_waitcnt vmcnt(19)
	v_lshlrev_b32_e32 v74, 16, v218
	v_and_b32_e32 v75, 0xffff0000, v218
	v_lshlrev_b32_e32 v68, 16, v219
	v_and_b32_e32 v69, 0xffff0000, v219
	v_lshlrev_b32_e32 v76, 16, v220
	v_and_b32_e32 v77, 0xffff0000, v220
	v_lshlrev_b32_e32 v70, 16, v221
	v_and_b32_e32 v71, 0xffff0000, v221
	v_pk_add_f32 v[64:65], v[64:65], v[68:69]
	v_pk_add_f32 v[62:63], v[62:63], v[74:75]
	v_pk_add_f32 v[68:69], v[60:61], v[70:71]
	v_pk_add_f32 v[70:71], v[58:59], v[76:77]
	v_cvt_pk_bf16_f32 v58, v62, v63
	v_cvt_pk_bf16_f32 v59, v64, v65
	v_cvt_pk_bf16_f32 v60, v70, v71
	v_cvt_pk_bf16_f32 v61, v68, v69
	global_store_dwordx4 v[72:73], v[58:61], off
	s_nop 1
	v_mul_f32_e32 v58, v63, v63
	v_mul_f32_e32 v59, v65, v65
	v_fmac_f32_e32 v58, v62, v62
	v_fmac_f32_e32 v59, v64, v64
	v_add_f32_e32 v58, v58, v59
	v_mul_f32_e32 v59, v71, v71
	v_fmac_f32_e32 v59, v70, v70
	v_add_f32_e32 v58, v59, v58
	v_mul_f32_e32 v59, v69, v69
	v_fmac_f32_e32 v59, v68, v68
	v_add_f32_e32 v68, v59, v58
	s_waitcnt vmcnt(19)
	v_lshlrev_b32_e32 v62, 16, v222
	v_and_b32_e32 v63, 0xffff0000, v222
	v_lshlrev_b32_e32 v58, 16, v223
	v_and_b32_e32 v59, 0xffff0000, v223
	v_lshlrev_b32_e32 v64, 16, v224
	v_and_b32_e32 v65, 0xffff0000, v224
	v_lshlrev_b32_e32 v60, 16, v225
	v_and_b32_e32 v61, 0xffff0000, v225
	v_pk_add_f32 v[56:57], v[56:57], v[58:59]
	v_pk_add_f32 v[54:55], v[54:55], v[62:63]
	v_pk_add_f32 v[58:59], v[52:53], v[60:61]
	v_pk_add_f32 v[60:61], v[50:51], v[64:65]
	v_cvt_pk_bf16_f32 v50, v54, v55
	v_cvt_pk_bf16_f32 v51, v56, v57
	v_cvt_pk_bf16_f32 v52, v60, v61
	v_cvt_pk_bf16_f32 v53, v58, v59
	global_store_dwordx4 v[72:73], v[50:53], off offset:256
	s_nop 1
	v_mul_f32_e32 v50, v55, v55
	v_mul_f32_e32 v51, v57, v57
	v_fmac_f32_e32 v50, v54, v54
	v_fmac_f32_e32 v51, v56, v56
	v_add_f32_e32 v50, v50, v51
	v_mul_f32_e32 v51, v61, v61
	v_fmac_f32_e32 v51, v60, v60
	v_add_f32_e32 v50, v51, v50
	v_mul_f32_e32 v51, v59, v59
	v_fmac_f32_e32 v51, v58, v58
	v_add_f32_e32 v50, v51, v50
	v_add_f32_e32 v50, v68, v50
	v_mov_b32_e32 v51, v50
	s_nop 1
	v_permlane16_swap_b32_e32 v50, v51
	v_add_f32_e32 v50, v50, v51
	v_mov_b32_e32 v51, v50
	s_nop 1
	v_permlane32_swap_b32_e32 v50, v51
	s_and_saveexec_b64 s[12:13], s[6:7]
	s_cbranch_execz .LBB0_331
	s_waitcnt lgkmcnt(0)
	v_add_f32_e32 v52, v50, v51
	v_lshlrev_b64 v[50:51], 6, v[66:67]
	v_lshl_add_u64 v[50:51], s[82:83], 0, v[50:51]
	v_lshl_add_u64 v[50:51], vcc, 2, v[50:51]
	s_lshl_b32 s60, s53, 2
	v_lshl_add_u64 v[50:51], v[50:51], 0, s[60:61]
	global_store_dword v[50:51], v52, off
.LBB0_331:
	s_or_b64 exec, exec, s[12:13]
	v_add_u32_e32 v50, 0x90, v154
	s_waitcnt lgkmcnt(0)
	v_ashrrev_i32_e32 v51, 31, v50
	v_lshlrev_b64 v[52:53], 11, v[50:51]
	v_lshl_add_u64 v[52:53], s[78:79], 0, v[52:53]
	v_lshl_add_u64 v[56:57], v[152:153], 1, v[52:53]
	s_waitcnt vmcnt(20)
	v_lshlrev_b32_e32 v58, 16, v226
	v_and_b32_e32 v59, 0xffff0000, v226
	v_lshlrev_b32_e32 v52, 16, v227
	v_and_b32_e32 v53, 0xffff0000, v227
	v_lshlrev_b32_e32 v60, 16, v228
	v_and_b32_e32 v61, 0xffff0000, v228
	v_lshlrev_b32_e32 v54, 16, v229
	v_and_b32_e32 v55, 0xffff0000, v229
	v_pk_add_f32 v[48:49], v[48:49], v[52:53]
	v_pk_add_f32 v[46:47], v[46:47], v[58:59]
	v_pk_add_f32 v[52:53], v[44:45], v[54:55]
	v_pk_add_f32 v[54:55], v[42:43], v[60:61]
	v_cvt_pk_bf16_f32 v42, v46, v47
	v_cvt_pk_bf16_f32 v43, v48, v49
	v_cvt_pk_bf16_f32 v44, v54, v55
	v_cvt_pk_bf16_f32 v45, v52, v53
	global_store_dwordx4 v[56:57], v[42:45], off
	s_nop 1
	v_mul_f32_e32 v42, v47, v47
	v_mul_f32_e32 v43, v49, v49
	v_fmac_f32_e32 v42, v46, v46
	v_fmac_f32_e32 v43, v48, v48
	v_add_f32_e32 v42, v42, v43
	v_mul_f32_e32 v43, v55, v55
	v_fmac_f32_e32 v43, v54, v54
	v_add_f32_e32 v42, v43, v42
	v_mul_f32_e32 v43, v53, v53
	v_fmac_f32_e32 v43, v52, v52
	v_add_f32_e32 v52, v43, v42
	s_waitcnt vmcnt(20)
	v_lshlrev_b32_e32 v46, 16, v230
	v_and_b32_e32 v47, 0xffff0000, v230
	v_lshlrev_b32_e32 v42, 16, v231
	v_and_b32_e32 v43, 0xffff0000, v231
	v_lshlrev_b32_e32 v48, 16, v232
	v_and_b32_e32 v49, 0xffff0000, v232
	v_lshlrev_b32_e32 v44, 16, v233
	v_and_b32_e32 v45, 0xffff0000, v233
	v_pk_add_f32 v[40:41], v[40:41], v[42:43]
	v_pk_add_f32 v[38:39], v[38:39], v[46:47]
	v_pk_add_f32 v[42:43], v[36:37], v[44:45]
	v_pk_add_f32 v[44:45], v[34:35], v[48:49]
	v_cvt_pk_bf16_f32 v34, v38, v39
	v_cvt_pk_bf16_f32 v35, v40, v41
	v_cvt_pk_bf16_f32 v36, v44, v45
	v_cvt_pk_bf16_f32 v37, v42, v43
	global_store_dwordx4 v[56:57], v[34:37], off offset:256
	s_nop 1
	v_mul_f32_e32 v34, v39, v39
	v_mul_f32_e32 v35, v41, v41
	v_fmac_f32_e32 v34, v38, v38
	v_fmac_f32_e32 v35, v40, v40
	v_add_f32_e32 v34, v34, v35
	v_mul_f32_e32 v35, v45, v45
	v_fmac_f32_e32 v35, v44, v44
	v_add_f32_e32 v34, v35, v34
	v_mul_f32_e32 v35, v43, v43
	v_fmac_f32_e32 v35, v42, v42
	v_add_f32_e32 v34, v35, v34
	v_add_f32_e32 v34, v52, v34
	v_mov_b32_e32 v35, v34
	s_nop 1
	v_permlane16_swap_b32_e32 v34, v35
	v_add_f32_e32 v34, v34, v35
	v_mov_b32_e32 v35, v34
	s_nop 1
	v_permlane32_swap_b32_e32 v34, v35
	s_and_saveexec_b64 s[12:13], s[6:7]
	s_cbranch_execz .LBB0_333
	s_waitcnt lgkmcnt(0)
	v_add_f32_e32 v36, v34, v35
	v_lshlrev_b64 v[34:35], 6, v[50:51]
	v_lshl_add_u64 v[34:35], s[82:83], 0, v[34:35]
	v_lshl_add_u64 v[34:35], vcc, 2, v[34:35]
	s_lshl_b32 s60, s53, 2
	v_lshl_add_u64 v[34:35], v[34:35], 0, s[60:61]
	global_store_dword v[34:35], v36, off
.LBB0_333:
	s_or_b64 exec, exec, s[12:13]
	v_add_u32_e32 v34, 0xa0, v154
	s_waitcnt lgkmcnt(0)
	v_ashrrev_i32_e32 v35, 31, v34
	v_lshlrev_b64 v[36:37], 11, v[34:35]
	v_lshl_add_u64 v[36:37], s[78:79], 0, v[36:37]
	v_lshl_add_u64 v[40:41], v[152:153], 1, v[36:37]
	s_waitcnt vmcnt(21)
	v_lshlrev_b32_e32 v42, 16, v234
	v_and_b32_e32 v43, 0xffff0000, v234
	v_lshlrev_b32_e32 v36, 16, v235
	v_and_b32_e32 v37, 0xffff0000, v235
	v_lshlrev_b32_e32 v44, 16, v236
	v_and_b32_e32 v45, 0xffff0000, v236
	v_lshlrev_b32_e32 v38, 16, v237
	v_and_b32_e32 v39, 0xffff0000, v237
	v_pk_add_f32 v[32:33], v[32:33], v[36:37]
	v_pk_add_f32 v[30:31], v[30:31], v[42:43]
	v_pk_add_f32 v[36:37], v[28:29], v[38:39]
	v_pk_add_f32 v[38:39], v[26:27], v[44:45]
	v_cvt_pk_bf16_f32 v26, v30, v31
	v_cvt_pk_bf16_f32 v27, v32, v33
	v_cvt_pk_bf16_f32 v28, v38, v39
	v_cvt_pk_bf16_f32 v29, v36, v37
	global_store_dwordx4 v[40:41], v[26:29], off
	s_nop 1
	v_mul_f32_e32 v26, v31, v31
	v_mul_f32_e32 v27, v33, v33
	v_fmac_f32_e32 v26, v30, v30
	v_fmac_f32_e32 v27, v32, v32
	v_add_f32_e32 v26, v26, v27
	v_mul_f32_e32 v27, v39, v39
	v_fmac_f32_e32 v27, v38, v38
	v_add_f32_e32 v26, v27, v26
	v_mul_f32_e32 v27, v37, v37
	v_fmac_f32_e32 v27, v36, v36
	v_add_f32_e32 v36, v27, v26
	s_waitcnt vmcnt(21)
	v_lshlrev_b32_e32 v30, 16, v238
	v_and_b32_e32 v31, 0xffff0000, v238
	v_lshlrev_b32_e32 v26, 16, v239
	v_and_b32_e32 v27, 0xffff0000, v239
	v_lshlrev_b32_e32 v32, 16, v240
	v_and_b32_e32 v33, 0xffff0000, v240
	v_lshlrev_b32_e32 v28, 16, v241
	v_and_b32_e32 v29, 0xffff0000, v241
	v_pk_add_f32 v[24:25], v[24:25], v[26:27]
	v_pk_add_f32 v[22:23], v[22:23], v[30:31]
	v_pk_add_f32 v[26:27], v[20:21], v[28:29]
	v_pk_add_f32 v[28:29], v[18:19], v[32:33]
	v_cvt_pk_bf16_f32 v18, v22, v23
	v_cvt_pk_bf16_f32 v19, v24, v25
	v_cvt_pk_bf16_f32 v20, v28, v29
	v_cvt_pk_bf16_f32 v21, v26, v27
	global_store_dwordx4 v[40:41], v[18:21], off offset:256
	s_nop 1
	v_mul_f32_e32 v18, v23, v23
	v_mul_f32_e32 v19, v25, v25
	v_fmac_f32_e32 v18, v22, v22
	v_fmac_f32_e32 v19, v24, v24
	v_add_f32_e32 v18, v18, v19
	v_mul_f32_e32 v19, v29, v29
	v_fmac_f32_e32 v19, v28, v28
	v_add_f32_e32 v18, v19, v18
	v_mul_f32_e32 v19, v27, v27
	v_fmac_f32_e32 v19, v26, v26
	v_add_f32_e32 v18, v19, v18
	v_add_f32_e32 v18, v36, v18
	v_mov_b32_e32 v19, v18
	s_nop 1
	v_permlane16_swap_b32_e32 v18, v19
	v_add_f32_e32 v18, v18, v19
	v_mov_b32_e32 v19, v18
	s_nop 1
	v_permlane32_swap_b32_e32 v18, v19
	s_and_saveexec_b64 s[12:13], s[6:7]
	s_cbranch_execz .LBB0_335
	s_waitcnt lgkmcnt(0)
	v_add_f32_e32 v20, v18, v19
	v_lshlrev_b64 v[18:19], 6, v[34:35]
	v_lshl_add_u64 v[18:19], s[82:83], 0, v[18:19]
	v_lshl_add_u64 v[18:19], vcc, 2, v[18:19]
	s_lshl_b32 s60, s53, 2
	v_lshl_add_u64 v[18:19], v[18:19], 0, s[60:61]
	global_store_dword v[18:19], v20, off
.LBB0_335:
	s_or_b64 exec, exec, s[12:13]
	v_add_u32_e32 v18, 0xb0, v154
	s_waitcnt lgkmcnt(0)
	v_ashrrev_i32_e32 v19, 31, v18
	v_lshlrev_b64 v[20:21], 11, v[18:19]
	v_lshl_add_u64 v[20:21], s[78:79], 0, v[20:21]
	v_lshl_add_u64 v[24:25], v[152:153], 1, v[20:21]
	s_waitcnt vmcnt(22)
	v_lshlrev_b32_e32 v26, 16, v242
	v_and_b32_e32 v27, 0xffff0000, v242
	v_lshlrev_b32_e32 v20, 16, v243
	v_and_b32_e32 v21, 0xffff0000, v243
	v_lshlrev_b32_e32 v28, 16, v244
	v_and_b32_e32 v29, 0xffff0000, v244
	v_lshlrev_b32_e32 v22, 16, v245
	v_and_b32_e32 v23, 0xffff0000, v245
	v_pk_add_f32 v[16:17], v[16:17], v[20:21]
	v_pk_add_f32 v[14:15], v[14:15], v[26:27]
	v_pk_add_f32 v[20:21], v[12:13], v[22:23]
	v_pk_add_f32 v[22:23], v[10:11], v[28:29]
	v_cvt_pk_bf16_f32 v10, v14, v15
	v_cvt_pk_bf16_f32 v11, v16, v17
	v_cvt_pk_bf16_f32 v12, v22, v23
	v_cvt_pk_bf16_f32 v13, v20, v21
	global_store_dwordx4 v[24:25], v[10:13], off
	s_nop 1
	v_mul_f32_e32 v10, v15, v15
	v_mul_f32_e32 v11, v17, v17
	v_fmac_f32_e32 v10, v14, v14
	v_fmac_f32_e32 v11, v16, v16
	v_add_f32_e32 v10, v10, v11
	v_mul_f32_e32 v11, v23, v23
	v_fmac_f32_e32 v11, v22, v22
	v_add_f32_e32 v10, v11, v10
	v_mul_f32_e32 v11, v21, v21
	v_fmac_f32_e32 v11, v20, v20
	v_add_f32_e32 v20, v11, v10
	s_waitcnt vmcnt(22)
	v_lshlrev_b32_e32 v14, 16, v246
	v_and_b32_e32 v15, 0xffff0000, v246
	v_lshlrev_b32_e32 v10, 16, v247
	v_and_b32_e32 v11, 0xffff0000, v247
	v_lshlrev_b32_e32 v16, 16, v248
	v_and_b32_e32 v17, 0xffff0000, v248
	v_lshlrev_b32_e32 v12, 16, v249
	v_and_b32_e32 v13, 0xffff0000, v249
	v_pk_add_f32 v[8:9], v[8:9], v[10:11]
	v_pk_add_f32 v[6:7], v[6:7], v[14:15]
	v_pk_add_f32 v[10:11], v[4:5], v[12:13]
	v_pk_add_f32 v[12:13], v[2:3], v[16:17]
	v_cvt_pk_bf16_f32 v2, v6, v7
	v_cvt_pk_bf16_f32 v3, v8, v9
	v_cvt_pk_bf16_f32 v4, v12, v13
	v_cvt_pk_bf16_f32 v5, v10, v11
	global_store_dwordx4 v[24:25], v[2:5], off offset:256
	s_nop 1
	v_mul_f32_e32 v2, v7, v7
	v_mul_f32_e32 v3, v9, v9
	v_fmac_f32_e32 v2, v6, v6
	v_fmac_f32_e32 v3, v8, v8
	v_add_f32_e32 v2, v2, v3
	v_mul_f32_e32 v3, v13, v13
	v_fmac_f32_e32 v3, v12, v12
	v_add_f32_e32 v2, v3, v2
	v_mul_f32_e32 v3, v11, v11
	v_fmac_f32_e32 v3, v10, v10
	v_add_f32_e32 v2, v3, v2
	v_add_f32_e32 v2, v20, v2
	v_mov_b32_e32 v3, v2
	s_nop 1
	v_permlane16_swap_b32_e32 v2, v3
	v_add_f32_e32 v2, v2, v3
	v_mov_b32_e32 v3, v2
	s_nop 1
	v_permlane32_swap_b32_e32 v2, v3
	s_and_saveexec_b64 s[12:13], s[6:7]
	s_cbranch_execz .LBB0_337
	s_waitcnt lgkmcnt(0)
	v_add_f32_e32 v4, v2, v3
	v_lshlrev_b64 v[2:3], 6, v[18:19]
	v_lshl_add_u64 v[2:3], s[82:83], 0, v[2:3]
	v_lshl_add_u64 v[2:3], vcc, 2, v[2:3]
	s_lshl_b32 s60, s53, 2
	v_lshl_add_u64 v[2:3], v[2:3], 0, s[60:61]
	global_store_dword v[2:3], v4, off

.Lfrain_issued:
	s_waitcnt vmcnt(0)
	s_mov_b64 s[8:9], s[2:3]
	v_cmp_gt_i64_e32 vcc, s[8:9], v[140:141]
	s_mov_b64 s[10:11], -1
	s_cbranch_vccnz .Lfrain_done
	v_pk_add_f32 v[16:17], v[16:17], v[20:21]
	v_pk_add_f32 v[14:15], v[14:15], v[18:19]
	v_cmp_lt_i32_e32 vcc, v172, v171
	v_add_f32_e32 v6, v14, v15
	v_add_f32_e32 v7, v16, v17
	v_add_f32_e32 v6, v6, v7
	s_nop 1
	v_mov_b32_dpp v7, v6 quad_perm:[1,0,3,2] row_mask:0xf bank_mask:0xf
	s_and_saveexec_b64 s[10:11], s[6:7]
	s_waitcnt lgkmcnt(0)
	v_add_f32_e32 v6, v6, v7
	v_fmamk_f32 v6, v6, 0x3a800000, v166
	v_rsq_f32_e32 v6, v6
	ds_write_b32 v5, v6
	s_or_b64 exec, exec, s[10:11]
	s_add_u32 s8, s8, s14
	s_addc_u32 s9, s9, s55
	v_cmp_gt_i64_e32 vcc, s[8:9], v[140:141]
	s_mov_b64 s[10:11], -1
	s_cbranch_vccnz .Lfrain_done
	v_pk_add_f32 v[24:25], v[24:25], v[28:29]
	v_pk_add_f32 v[22:23], v[22:23], v[26:27]
	v_cmp_lt_i32_e32 vcc, v172, v171
	v_add_f32_e32 v6, v22, v23
	v_add_f32_e32 v7, v24, v25
	v_add_f32_e32 v6, v6, v7
	s_nop 1
	v_mov_b32_dpp v7, v6 quad_perm:[1,0,3,2] row_mask:0xf bank_mask:0xf
	s_and_saveexec_b64 s[10:11], s[6:7]
	s_waitcnt lgkmcnt(0)
	v_add_f32_e32 v6, v6, v7
	v_fmamk_f32 v6, v6, 0x3a800000, v166
	v_rsq_f32_e32 v6, v6
	ds_write_b32 v5, v6 offset:1024
	s_or_b64 exec, exec, s[10:11]
	s_add_u32 s8, s8, s14
	s_addc_u32 s9, s9, s55
	v_cmp_gt_i64_e32 vcc, s[8:9], v[140:141]
	s_mov_b64 s[10:11], -1
	s_cbranch_vccnz .Lfrain_done
	v_pk_add_f32 v[32:33], v[32:33], v[36:37]
	v_pk_add_f32 v[30:31], v[30:31], v[34:35]
	v_cmp_lt_i32_e32 vcc, v172, v171
	v_add_f32_e32 v6, v30, v31
	v_add_f32_e32 v7, v32, v33
	v_add_f32_e32 v6, v6, v7
	s_nop 1
	v_mov_b32_dpp v7, v6 quad_perm:[1,0,3,2] row_mask:0xf bank_mask:0xf
	s_and_saveexec_b64 s[10:11], s[6:7]
	s_waitcnt lgkmcnt(0)
	v_add_f32_e32 v6, v6, v7
	v_fmamk_f32 v6, v6, 0x3a800000, v166
	v_rsq_f32_e32 v6, v6
	ds_write_b32 v5, v6 offset:2048
	s_or_b64 exec, exec, s[10:11]
	s_add_u32 s8, s8, s14
	s_addc_u32 s9, s9, s55
	v_cmp_gt_i64_e32 vcc, s[8:9], v[140:141]
	s_mov_b64 s[10:11], -1
	s_cbranch_vccnz .Lfrain_done
	v_pk_add_f32 v[40:41], v[40:41], v[44:45]
	v_pk_add_f32 v[38:39], v[38:39], v[42:43]
	v_cmp_lt_i32_e32 vcc, v172, v171
	v_add_f32_e32 v6, v38, v39
	v_add_f32_e32 v7, v40, v41
	v_add_f32_e32 v6, v6, v7
	s_nop 1
	v_mov_b32_dpp v7, v6 quad_perm:[1,0,3,2] row_mask:0xf bank_mask:0xf
	s_and_saveexec_b64 s[10:11], s[6:7]
	s_waitcnt lgkmcnt(0)
	v_add_f32_e32 v6, v6, v7
	v_fmamk_f32 v6, v6, 0x3a800000, v166
	v_rsq_f32_e32 v6, v6
	ds_write_b32 v5, v6 offset:3072
	s_or_b64 exec, exec, s[10:11]
	s_add_u32 s8, s8, s14
	s_addc_u32 s9, s9, s55
	v_cmp_gt_i64_e32 vcc, s[8:9], v[140:141]
	s_mov_b64 s[10:11], -1
	s_cbranch_vccnz .Lfrain_done
	v_pk_add_f32 v[48:49], v[48:49], v[52:53]
	v_pk_add_f32 v[46:47], v[46:47], v[50:51]
	v_cmp_lt_i32_e32 vcc, v172, v171
	v_add_f32_e32 v6, v46, v47
	v_add_f32_e32 v7, v48, v49
	v_add_f32_e32 v6, v6, v7
	s_nop 1
	v_mov_b32_dpp v7, v6 quad_perm:[1,0,3,2] row_mask:0xf bank_mask:0xf
	s_and_saveexec_b64 s[10:11], s[6:7]
	s_waitcnt lgkmcnt(0)
	v_add_f32_e32 v6, v6, v7
	v_fmamk_f32 v6, v6, 0x3a800000, v166
	v_rsq_f32_e32 v6, v6
	ds_write_b32 v5, v6 offset:4096
	s_or_b64 exec, exec, s[10:11]
	s_add_u32 s8, s8, s14
	s_addc_u32 s9, s9, s55
